# code placement: every back-to-back MFMA run in the six GEMM k-loops aligned to 8 bytes (.p2align 3; half of them sat at 4 mod 8)
# speedup vs baseline: 1.0006x; 1.0006x over previous
; #define PG8_STAGE(bufoff, gbase, voff) do { _Pragma("unroll") for (int _i = 0; _i < 2; ++_i) \
;         __builtin_amdgcn_global_load_lds((const unsigned*)((const char*)(gbase) + (voff)[_i]), (PG8_LAS unsigned*)(lds + (bufoff) + ldsw + _i * 8192), 16, 0, 0); } while (0)
; #define PG8_LDA(dst, b, h) do { _Pragma("unroll") for (int m = 0; m < 4; ++m) _Pragma("unroll") for (int k = 0; k < 2; ++k) dst[m][k] = *(const PG8_LAS bf16x8*)(lds + PG8_SA(b, h) + aoff + m * 2048 + k * 1024); } while (0)
; #define PG8_LDB(dst, b, h) do { _Pragma("unroll") for (int n = 0; n < 2; ++n) _Pragma("unroll") for (int k = 0; k < 2; ++k) dst[n][k] = *(const PG8_LAS bf16x8*)(lds + PG8_SB(b, h) + boff + n * 2048 + k * 1024); } while (0)
; #define PG8_MMA(ai, bj, At, Bt) do { __builtin_amdgcn_s_setprio(1); _Pragma("unroll") for (int m = 0; m < 4; ++m) _Pragma("unroll") for (int n = 0; n < 2; ++n) _Pragma("unroll") for (int k = 0; k < 2; ++k) \
;         acc[ai][bj][m][n] = __builtin_amdgcn_mfma_f32_16x16x32_bf16(Bt[n][k], At[m][k], acc[ai][bj][m][n], 0, 0, 0); __builtin_amdgcn_s_setprio(0); } while (0)
; #define PG8_WAIT_V(n) asm volatile("s_waitcnt vmcnt(" #n ")" ::: "memory")
; #define PG8_WAIT_L(n) asm volatile("s_waitcnt lgkmcnt(" #n ")" ::: "memory")
; #define PG8_BAR __builtin_amdgcn_s_barrier()
; #define PG8_SCHED __builtin_amdgcn_sched_barrier(0)
; template <class Epi, class Sched, bool ALIGN_EPI = false, bool SP2 = false>
; __device__ __forceinline__ void gemm_phase(PG8_LAS unsigned char* lds, const Gemm g, const Sched& S, const Epi& E) {
;     ...
;             PG8_LDB(B0, 0, 0); PG8_LDB(B1, 0, 1); PG8_SCHED; PG8_LDA(At, 0, 0); PG8_STAGE(PG8_SA(1, 1), a1 + hstepA, voffA);
;             PG8_WAIT_V(8); PG8_WAIT_L(0); PG8_BAR; PG8_MMA(0, 0, At, B0); PG8_MMA(0, 1, At, B1); PG8_BAR; PG8_SCHED;
;             PG8_LDA(At, 0, 1); PG8_STAGE(PG8_SB(0, 0), b2, voffB); PG8_STAGE(PG8_SB(0, 1), b2 + hstepB, voffB); PG8_STAGE(PG8_SA(0, 0), a2, voffA);
;             PG8_WAIT_V(8); PG8_WAIT_L(0); PG8_BAR; PG8_MMA(1, 0, At, B0); PG8_MMA(1, 1, At, B1); PG8_BAR; PG8_SCHED;
.Lsp_LBB0_365:
.LBB0_365:
	ds_read_b128 v[154:157], v169
	ds_read_b128 v[158:161], v169 offset:1024
	ds_read_b128 v[162:165], v169 offset:2048
	ds_read_b128 v[174:177], v169 offset:3072
	ds_read_b128 v[178:181], v170
	ds_read_b128 v[182:185], v170 offset:1024
	ds_read_b128 v[186:189], v170 offset:2048
	ds_read_b128 v[190:193], v170 offset:3072
	s_add_u32 s24, s60, 0xfff00080
	s_addc_u32 s25, s61, -1
	s_cmp_eq_u32 s73, 60
	s_cselect_b32 s25, s9, s25
	s_cselect_b32 s24, s10, s24
	s_cselect_b32 s67, s11, s72
	s_cselect_b32 s66, s19, s21
	s_add_i32 m0, s27, 0xc000
	ds_read_b128 v[194:197], v171
	ds_read_b128 v[198:201], v171 offset:1024
	ds_read_b128 v[202:205], v171 offset:2048
	ds_read_b128 v[206:209], v171 offset:3072
	ds_read_b128 v[210:213], v171 offset:4096
	ds_read_b128 v[214:217], v171 offset:5120
	ds_read_b128 v[218:221], v171 offset:6144
	ds_read_b128 v[222:225], v171 offset:7168
	global_load_lds_dwordx4 v146, s[60:61]
	s_add_i32 m0, s27, 0xe000
	s_nop 0
	global_load_lds_dwordx4 v148, s[60:61]
	s_waitcnt vmcnt(8)
	s_waitcnt lgkmcnt(0)
	s_barrier
	s_waitcnt lgkmcnt(0)
	.p2align 3
	v_mfma_f32_16x16x32_bf16 v[126:129], v[154:157], v[194:197], v[126:129]
	v_mfma_f32_16x16x32_bf16 v[122:125], v[162:165], v[194:197], v[122:125]
	v_mfma_f32_16x16x32_bf16 v[110:113], v[154:157], v[202:205], v[110:113]
	v_mfma_f32_16x16x32_bf16 v[106:109], v[162:165], v[202:205], v[106:109]
	v_mfma_f32_16x16x32_bf16 v[94:97], v[154:157], v[210:213], v[94:97]
	v_mfma_f32_16x16x32_bf16 v[90:93], v[162:165], v[210:213], v[90:93]
	v_mfma_f32_16x16x32_bf16 v[78:81], v[154:157], v[218:221], v[78:81]
	v_mfma_f32_16x16x32_bf16 v[74:77], v[162:165], v[218:221], v[74:77]
	v_mfma_f32_16x16x32_bf16 v[126:129], v[158:161], v[198:201], v[126:129]
	v_mfma_f32_16x16x32_bf16 v[122:125], v[174:177], v[198:201], v[122:125]
	v_mfma_f32_16x16x32_bf16 v[110:113], v[158:161], v[206:209], v[110:113]
	v_mfma_f32_16x16x32_bf16 v[106:109], v[174:177], v[206:209], v[106:109]
	v_mfma_f32_16x16x32_bf16 v[94:97], v[158:161], v[214:217], v[94:97]
	v_mfma_f32_16x16x32_bf16 v[90:93], v[174:177], v[214:217], v[90:93]
	v_mfma_f32_16x16x32_bf16 v[78:81], v[158:161], v[222:225], v[78:81]
	v_mfma_f32_16x16x32_bf16 v[74:77], v[174:177], v[222:225], v[74:77]
	v_mfma_f32_16x16x32_bf16 v[118:121], v[178:181], v[194:197], v[118:121]
	v_mfma_f32_16x16x32_bf16 v[114:117], v[186:189], v[194:197], v[114:117]
	v_mfma_f32_16x16x32_bf16 v[102:105], v[178:181], v[202:205], v[102:105]
	v_mfma_f32_16x16x32_bf16 v[98:101], v[186:189], v[202:205], v[98:101]
	v_mfma_f32_16x16x32_bf16 v[86:89], v[178:181], v[210:213], v[86:89]
	v_mfma_f32_16x16x32_bf16 v[82:85], v[186:189], v[210:213], v[82:85]
	v_mfma_f32_16x16x32_bf16 v[70:73], v[178:181], v[218:221], v[70:73]
	v_mfma_f32_16x16x32_bf16 v[66:69], v[186:189], v[218:221], v[66:69]
	v_mfma_f32_16x16x32_bf16 v[118:121], v[182:185], v[198:201], v[118:121]
	v_mfma_f32_16x16x32_bf16 v[114:117], v[190:193], v[198:201], v[114:117]
	v_mfma_f32_16x16x32_bf16 v[102:105], v[182:185], v[206:209], v[102:105]
	v_mfma_f32_16x16x32_bf16 v[98:101], v[190:193], v[206:209], v[98:101]
	v_mfma_f32_16x16x32_bf16 v[86:89], v[182:185], v[214:217], v[86:89]
	v_mfma_f32_16x16x32_bf16 v[82:85], v[190:193], v[214:217], v[82:85]
	v_mfma_f32_16x16x32_bf16 v[70:73], v[182:185], v[222:225], v[70:73]
	v_mfma_f32_16x16x32_bf16 v[66:69], v[190:193], v[222:225], v[66:69]
	s_barrier
	s_add_i32 s74, s47, s26
	s_add_u32 s98, s66, 0x80
	s_addc_u32 s99, s67, 0
	s_add_u32 s100, s24, 0x80
	s_addc_u32 s101, s25, 0
	s_mov_b32 m0, s74
	ds_read_b128 v[194:197], v171 offset:16384
	ds_read_b128 v[198:201], v171 offset:17408
	ds_read_b128 v[202:205], v171 offset:18432
	ds_read_b128 v[206:209], v171 offset:19456
	ds_read_b128 v[210:213], v171 offset:20480
	ds_read_b128 v[214:217], v171 offset:21504
	ds_read_b128 v[218:221], v171 offset:22528
	ds_read_b128 v[222:225], v171 offset:23552
	global_load_lds_dwordx4 v132, s[66:67]
	s_add_i32 m0, s74, 0x2000
	s_add_u32 s74, s66, 0x100000
	s_addc_u32 s75, s67, 0
	s_add_i32 s76, s48, s26
	global_load_lds_dwordx4 v136, s[66:67]
	s_mov_b32 m0, s76
	s_nop 0
	global_load_lds_dwordx4 v132, s[74:75]
	s_add_i32 m0, s76, 0x2000
	s_nop 0
	global_load_lds_dwordx4 v136, s[74:75]
	s_mov_b32 m0, s27
	s_nop 0
	global_load_lds_dwordx4 v130, s[24:25]
	s_mov_b32 m0, s34
	s_nop 0
	global_load_lds_dwordx4 v134, s[24:25]
	s_waitcnt vmcnt(8)
	s_waitcnt lgkmcnt(0)
	s_barrier
	s_waitcnt lgkmcnt(0)
	.p2align 3
	v_mfma_f32_16x16x32_bf16 v[62:65], v[154:157], v[194:197], v[62:65]
	v_mfma_f32_16x16x32_bf16 v[58:61], v[162:165], v[194:197], v[58:61]
	v_mfma_f32_16x16x32_bf16 v[46:49], v[154:157], v[202:205], v[46:49]
	v_mfma_f32_16x16x32_bf16 v[42:45], v[162:165], v[202:205], v[42:45]
	v_mfma_f32_16x16x32_bf16 v[30:33], v[154:157], v[210:213], v[30:33]
	v_mfma_f32_16x16x32_bf16 v[26:29], v[162:165], v[210:213], v[26:29]
	v_mfma_f32_16x16x32_bf16 v[14:17], v[154:157], v[218:221], v[14:17]
	v_mfma_f32_16x16x32_bf16 v[10:13], v[162:165], v[218:221], v[10:13]
	v_mfma_f32_16x16x32_bf16 v[62:65], v[158:161], v[198:201], v[62:65]
	v_mfma_f32_16x16x32_bf16 v[58:61], v[174:177], v[198:201], v[58:61]
	v_mfma_f32_16x16x32_bf16 v[46:49], v[158:161], v[206:209], v[46:49]
	v_mfma_f32_16x16x32_bf16 v[42:45], v[174:177], v[206:209], v[42:45]
	v_mfma_f32_16x16x32_bf16 v[30:33], v[158:161], v[214:217], v[30:33]
	v_mfma_f32_16x16x32_bf16 v[26:29], v[174:177], v[214:217], v[26:29]
	v_mfma_f32_16x16x32_bf16 v[14:17], v[158:161], v[222:225], v[14:17]
	v_mfma_f32_16x16x32_bf16 v[10:13], v[174:177], v[222:225], v[10:13]
	v_mfma_f32_16x16x32_bf16 v[54:57], v[178:181], v[194:197], v[54:57]
	v_mfma_f32_16x16x32_bf16 v[50:53], v[186:189], v[194:197], v[50:53]
	v_mfma_f32_16x16x32_bf16 v[38:41], v[178:181], v[202:205], v[38:41]
	v_mfma_f32_16x16x32_bf16 v[34:37], v[186:189], v[202:205], v[34:37]
	v_mfma_f32_16x16x32_bf16 v[22:25], v[178:181], v[210:213], v[22:25]
	v_mfma_f32_16x16x32_bf16 v[18:21], v[186:189], v[210:213], v[18:21]
	v_mfma_f32_16x16x32_bf16 v[6:9], v[178:181], v[218:221], v[6:9]
	v_mfma_f32_16x16x32_bf16 v[2:5], v[186:189], v[218:221], v[2:5]
	v_mfma_f32_16x16x32_bf16 v[54:57], v[182:185], v[198:201], v[54:57]
	v_mfma_f32_16x16x32_bf16 v[50:53], v[190:193], v[198:201], v[50:53]
	v_mfma_f32_16x16x32_bf16 v[38:41], v[182:185], v[206:209], v[38:41]
	v_mfma_f32_16x16x32_bf16 v[34:37], v[190:193], v[206:209], v[34:37]
	v_mfma_f32_16x16x32_bf16 v[22:25], v[182:185], v[214:217], v[22:25]
	v_mfma_f32_16x16x32_bf16 v[18:21], v[190:193], v[214:217], v[18:21]
	v_mfma_f32_16x16x32_bf16 v[6:9], v[182:185], v[222:225], v[6:9]
	v_mfma_f32_16x16x32_bf16 v[2:5], v[190:193], v[222:225], v[2:5]
	s_barrier
; #define PG8_STAGE(bufoff, gbase, voff) do { _Pragma("unroll") for (int _i = 0; _i < 2; ++_i) \
;         __builtin_amdgcn_global_load_lds((const unsigned*)((const char*)(gbase) + (voff)[_i]), (PG8_LAS unsigned*)(lds + (bufoff) + ldsw + _i * 8192), 16, 0, 0); } while (0)
; #define PG8_LDA(dst, b, h) do { _Pragma("unroll") for (int m = 0; m < 4; ++m) _Pragma("unroll") for (int k = 0; k < 2; ++k) dst[m][k] = *(const PG8_LAS bf16x8*)(lds + PG8_SA(b, h) + aoff + m * 2048 + k * 1024); } while (0)
; #define PG8_LDB(dst, b, h) do { _Pragma("unroll") for (int n = 0; n < 2; ++n) _Pragma("unroll") for (int k = 0; k < 2; ++k) dst[n][k] = *(const PG8_LAS bf16x8*)(lds + PG8_SB(b, h) + boff + n * 2048 + k * 1024); } while (0)
; #define PG8_MMA(ai, bj, At, Bt) do { __builtin_amdgcn_s_setprio(1); _Pragma("unroll") for (int m = 0; m < 4; ++m) _Pragma("unroll") for (int n = 0; n < 2; ++n) _Pragma("unroll") for (int k = 0; k < 2; ++k) \
;         acc[ai][bj][m][n] = __builtin_amdgcn_mfma_f32_16x16x32_bf16(Bt[n][k], At[m][k], acc[ai][bj][m][n], 0, 0, 0); __builtin_amdgcn_s_setprio(0); } while (0)
; #define PG8_WAIT_V(n) asm volatile("s_waitcnt vmcnt(" #n ")" ::: "memory")
; #define PG8_WAIT_L(n) asm volatile("s_waitcnt lgkmcnt(" #n ")" ::: "memory")
; #define PG8_BAR __builtin_amdgcn_s_barrier()
; #define PG8_SCHED __builtin_amdgcn_sched_barrier(0)
; template <class Epi, class Sched, bool ALIGN_EPI = false, bool SP2 = false>
; __device__ __forceinline__ void gemm_phase(PG8_LAS unsigned char* lds, const Gemm g, const Sched& S, const Epi& E) {
;     ...
;             PG8_LDB(B0, 1, 0); PG8_LDB(B1, 1, 1); PG8_SCHED; PG8_LDA(At, 1, 0); PG8_STAGE(PG8_SA(0, 1), a2 + hstepA, voffA);
;             PG8_WAIT_V(8); PG8_WAIT_L(0); PG8_BAR; PG8_MMA(0, 0, At, B0); PG8_MMA(0, 1, At, B1); PG8_BAR; PG8_SCHED;
;             PG8_LDA(At, 1, 1); PG8_STAGE(PG8_SB(1, 0), b3, voffB); PG8_STAGE(PG8_SB(1, 1), b3 + hstepB, voffB); PG8_STAGE(PG8_SA(1, 0), a3, voffA);
;             PG8_WAIT_V(8); PG8_WAIT_L(0); PG8_BAR; PG8_MMA(1, 0, At, B0); PG8_MMA(1, 1, At, B1); PG8_BAR; PG8_SCHED;
	s_add_i32 s74, 0, 0x18000
	v_add_u32_e32 v138, s74, v141
	s_add_i32 s75, 0, 0x1c000
	ds_read_b128 v[154:157], v138
	ds_read_b128 v[158:161], v138 offset:1024
	ds_read_b128 v[162:165], v138 offset:2048
	ds_read_b128 v[174:177], v138 offset:3072
	v_add_u32_e32 v138, s75, v141
	ds_read_b128 v[178:181], v138
	ds_read_b128 v[182:185], v138 offset:1024
	ds_read_b128 v[186:189], v138 offset:2048
	ds_read_b128 v[190:193], v138 offset:3072
	s_add_u32 s24, s24, 0x100000
	s_addc_u32 s25, s25, 0
	s_mov_b32 m0, s35
	ds_read_b128 v[194:197], v171 offset:32768
	ds_read_b128 v[198:201], v171 offset:33792
	ds_read_b128 v[202:205], v171 offset:34816
	ds_read_b128 v[206:209], v171 offset:35840
	ds_read_b128 v[210:213], v171 offset:36864
	ds_read_b128 v[214:217], v171 offset:37888
	ds_read_b128 v[218:221], v171 offset:38912
	ds_read_b128 v[222:225], v171 offset:39936
	global_load_lds_dwordx4 v130, s[24:25]
	s_mov_b32 m0, s36
	s_nop 0
	global_load_lds_dwordx4 v134, s[24:25]
	s_waitcnt vmcnt(8)
	s_waitcnt lgkmcnt(0)
	s_barrier
	s_waitcnt lgkmcnt(0)
	.p2align 3
	v_mfma_f32_16x16x32_bf16 v[126:129], v[154:157], v[194:197], v[126:129]
	v_mfma_f32_16x16x32_bf16 v[122:125], v[162:165], v[194:197], v[122:125]
	v_mfma_f32_16x16x32_bf16 v[110:113], v[154:157], v[202:205], v[110:113]
	v_mfma_f32_16x16x32_bf16 v[106:109], v[162:165], v[202:205], v[106:109]
	v_mfma_f32_16x16x32_bf16 v[94:97], v[154:157], v[210:213], v[94:97]
	v_mfma_f32_16x16x32_bf16 v[90:93], v[162:165], v[210:213], v[90:93]
	v_mfma_f32_16x16x32_bf16 v[78:81], v[154:157], v[218:221], v[78:81]
	v_mfma_f32_16x16x32_bf16 v[74:77], v[162:165], v[218:221], v[74:77]
	v_mfma_f32_16x16x32_bf16 v[126:129], v[158:161], v[198:201], v[126:129]
	v_mfma_f32_16x16x32_bf16 v[122:125], v[174:177], v[198:201], v[122:125]
	v_mfma_f32_16x16x32_bf16 v[110:113], v[158:161], v[206:209], v[110:113]
	v_mfma_f32_16x16x32_bf16 v[106:109], v[174:177], v[206:209], v[106:109]
	v_mfma_f32_16x16x32_bf16 v[94:97], v[158:161], v[214:217], v[94:97]
	v_mfma_f32_16x16x32_bf16 v[90:93], v[174:177], v[214:217], v[90:93]
	v_mfma_f32_16x16x32_bf16 v[78:81], v[158:161], v[222:225], v[78:81]
	v_mfma_f32_16x16x32_bf16 v[74:77], v[174:177], v[222:225], v[74:77]
	v_mfma_f32_16x16x32_bf16 v[118:121], v[178:181], v[194:197], v[118:121]
	v_mfma_f32_16x16x32_bf16 v[114:117], v[186:189], v[194:197], v[114:117]
	v_mfma_f32_16x16x32_bf16 v[102:105], v[178:181], v[202:205], v[102:105]
	v_mfma_f32_16x16x32_bf16 v[98:101], v[186:189], v[202:205], v[98:101]
	v_mfma_f32_16x16x32_bf16 v[86:89], v[178:181], v[210:213], v[86:89]
	v_mfma_f32_16x16x32_bf16 v[82:85], v[186:189], v[210:213], v[82:85]
	v_mfma_f32_16x16x32_bf16 v[70:73], v[178:181], v[218:221], v[70:73]
	v_mfma_f32_16x16x32_bf16 v[66:69], v[186:189], v[218:221], v[66:69]
	v_mfma_f32_16x16x32_bf16 v[118:121], v[182:185], v[198:201], v[118:121]
	v_mfma_f32_16x16x32_bf16 v[114:117], v[190:193], v[198:201], v[114:117]
	v_mfma_f32_16x16x32_bf16 v[102:105], v[182:185], v[206:209], v[102:105]
	v_mfma_f32_16x16x32_bf16 v[98:101], v[190:193], v[206:209], v[98:101]
	v_mfma_f32_16x16x32_bf16 v[86:89], v[182:185], v[214:217], v[86:89]
	v_mfma_f32_16x16x32_bf16 v[82:85], v[190:193], v[214:217], v[82:85]
	v_mfma_f32_16x16x32_bf16 v[70:73], v[182:185], v[222:225], v[70:73]
	v_mfma_f32_16x16x32_bf16 v[66:69], v[190:193], v[222:225], v[66:69]
	s_barrier
	s_add_i32 s24, s74, s26
	s_mov_b32 m0, s24
	ds_read_b128 v[194:197], v171 offset:49152
	ds_read_b128 v[198:201], v171 offset:50176
	ds_read_b128 v[202:205], v171 offset:51200
	ds_read_b128 v[206:209], v171 offset:52224
	ds_read_b128 v[210:213], v171 offset:53248
	ds_read_b128 v[214:217], v171 offset:54272
	ds_read_b128 v[218:221], v171 offset:55296
	ds_read_b128 v[222:225], v171 offset:56320
	global_load_lds_dwordx4 v132, s[98:99]
	s_add_i32 m0, s24, 0x2000
	s_add_u32 s24, s66, 0x100080
	s_addc_u32 s25, s67, 0
	s_add_i32 s66, s75, s26
	global_load_lds_dwordx4 v136, s[98:99]
	s_mov_b32 m0, s66
	s_nop 0
	global_load_lds_dwordx4 v132, s[24:25]
	s_add_i32 m0, s66, 0x2000
	s_nop 0
	global_load_lds_dwordx4 v136, s[24:25]
	s_mov_b32 m0, s42
	s_nop 0
	global_load_lds_dwordx4 v130, s[100:101]
	s_mov_b32 m0, s43
	s_nop 0
	global_load_lds_dwordx4 v134, s[100:101]
	s_waitcnt vmcnt(8)
	s_waitcnt lgkmcnt(0)
	s_barrier
	s_waitcnt lgkmcnt(0)
	.p2align 3
	v_mfma_f32_16x16x32_bf16 v[62:65], v[154:157], v[194:197], v[62:65]
	v_mfma_f32_16x16x32_bf16 v[58:61], v[162:165], v[194:197], v[58:61]
	v_mfma_f32_16x16x32_bf16 v[46:49], v[154:157], v[202:205], v[46:49]
	v_mfma_f32_16x16x32_bf16 v[42:45], v[162:165], v[202:205], v[42:45]
	v_mfma_f32_16x16x32_bf16 v[30:33], v[154:157], v[210:213], v[30:33]
	v_mfma_f32_16x16x32_bf16 v[26:29], v[162:165], v[210:213], v[26:29]
	v_mfma_f32_16x16x32_bf16 v[14:17], v[154:157], v[218:221], v[14:17]
	v_mfma_f32_16x16x32_bf16 v[10:13], v[162:165], v[218:221], v[10:13]
	v_mfma_f32_16x16x32_bf16 v[62:65], v[158:161], v[198:201], v[62:65]
	v_mfma_f32_16x16x32_bf16 v[58:61], v[174:177], v[198:201], v[58:61]
	v_mfma_f32_16x16x32_bf16 v[46:49], v[158:161], v[206:209], v[46:49]
	v_mfma_f32_16x16x32_bf16 v[42:45], v[174:177], v[206:209], v[42:45]
	v_mfma_f32_16x16x32_bf16 v[30:33], v[158:161], v[214:217], v[30:33]
	v_mfma_f32_16x16x32_bf16 v[26:29], v[174:177], v[214:217], v[26:29]
	v_mfma_f32_16x16x32_bf16 v[14:17], v[158:161], v[222:225], v[14:17]
	v_mfma_f32_16x16x32_bf16 v[10:13], v[174:177], v[222:225], v[10:13]
	v_mfma_f32_16x16x32_bf16 v[54:57], v[178:181], v[194:197], v[54:57]
	v_mfma_f32_16x16x32_bf16 v[50:53], v[186:189], v[194:197], v[50:53]
	v_mfma_f32_16x16x32_bf16 v[38:41], v[178:181], v[202:205], v[38:41]
	v_mfma_f32_16x16x32_bf16 v[34:37], v[186:189], v[202:205], v[34:37]
	v_mfma_f32_16x16x32_bf16 v[22:25], v[178:181], v[210:213], v[22:25]
	v_mfma_f32_16x16x32_bf16 v[18:21], v[186:189], v[210:213], v[18:21]
	v_mfma_f32_16x16x32_bf16 v[6:9], v[178:181], v[218:221], v[6:9]
	v_mfma_f32_16x16x32_bf16 v[2:5], v[186:189], v[218:221], v[2:5]
	v_mfma_f32_16x16x32_bf16 v[54:57], v[182:185], v[198:201], v[54:57]
	v_mfma_f32_16x16x32_bf16 v[50:53], v[190:193], v[198:201], v[50:53]
	v_mfma_f32_16x16x32_bf16 v[38:41], v[182:185], v[206:209], v[38:41]
	v_mfma_f32_16x16x32_bf16 v[34:37], v[190:193], v[206:209], v[34:37]
	v_mfma_f32_16x16x32_bf16 v[22:25], v[182:185], v[214:217], v[22:25]
	v_mfma_f32_16x16x32_bf16 v[18:21], v[190:193], v[214:217], v[18:21]
	v_mfma_f32_16x16x32_bf16 v[6:9], v[182:185], v[222:225], v[6:9]
	v_mfma_f32_16x16x32_bf16 v[2:5], v[190:193], v[222:225], v[2:5]
	s_barrier
	s_add_i32 s73, s73, 2
	s_add_u32 s60, s60, 0x100
	s_addc_u32 s61, s61, 0
	s_add_u32 s21, s21, 0x100
	s_addc_u32 s72, s72, 0
	s_cmp_gt_u32 s73, 61
	s_cbranch_scc0 .LBB0_365
	s_setprio 0
	s_and_b64 vcc, exec, s[16:17]
	s_cbranch_vccz .LBB0_368
	s_barrier

; #define PG8_STAGE(bufoff, gbase, voff) do { _Pragma("unroll") for (int _i = 0; _i < 2; ++_i) \
;         __builtin_amdgcn_global_load_lds((const unsigned*)((const char*)(gbase) + (voff)[_i]), (PG8_LAS unsigned*)(lds + (bufoff) + ldsw + _i * 8192), 16, 0, 0); } while (0)
; #define PG8_LDA(dst, b, h) do { _Pragma("unroll") for (int m = 0; m < 4; ++m) _Pragma("unroll") for (int k = 0; k < 2; ++k) dst[m][k] = *(const PG8_LAS bf16x8*)(lds + PG8_SA(b, h) + aoff + m * 2048 + k * 1024); } while (0)
; #define PG8_LDB(dst, b, h) do { _Pragma("unroll") for (int n = 0; n < 2; ++n) _Pragma("unroll") for (int k = 0; k < 2; ++k) dst[n][k] = *(const PG8_LAS bf16x8*)(lds + PG8_SB(b, h) + boff + n * 2048 + k * 1024); } while (0)
; #define PG8_MMA(ai, bj, At, Bt) do { __builtin_amdgcn_s_setprio(1); _Pragma("unroll") for (int m = 0; m < 4; ++m) _Pragma("unroll") for (int n = 0; n < 2; ++n) _Pragma("unroll") for (int k = 0; k < 2; ++k) \
;         acc[ai][bj][m][n] = __builtin_amdgcn_mfma_f32_16x16x32_bf16(Bt[n][k], At[m][k], acc[ai][bj][m][n], 0, 0, 0); __builtin_amdgcn_s_setprio(0); } while (0)
; #define PG8_WAIT_V(n) asm volatile("s_waitcnt vmcnt(" #n ")" ::: "memory")
; #define PG8_WAIT_L(n) asm volatile("s_waitcnt lgkmcnt(" #n ")" ::: "memory")
; #define PG8_BAR __builtin_amdgcn_s_barrier()
; #define PG8_SCHED __builtin_amdgcn_sched_barrier(0)
; template <class Epi, class Sched, bool ALIGN_EPI = false, bool SP2 = false>
; __device__ __forceinline__ void gemm_phase(PG8_LAS unsigned char* lds, const Gemm g, const Sched& S, const Epi& E) {
;     ...
;             PG8_LDB(B0, 0, 0); PG8_LDB(B1, 0, 1); PG8_SCHED; PG8_LDA(At, 0, 0); PG8_STAGE(PG8_SA(1, 1), a1 + hstepA, voffA);
;             PG8_WAIT_V(8); PG8_WAIT_L(0); PG8_BAR; PG8_MMA(0, 0, At, B0); PG8_MMA(0, 1, At, B1); PG8_BAR; PG8_SCHED;
;             PG8_LDA(At, 0, 1); PG8_STAGE(PG8_SB(0, 0), b2, voffB); PG8_STAGE(PG8_SB(0, 1), b2 + hstepB, voffB); PG8_STAGE(PG8_SA(0, 0), a2, voffA);
;             PG8_WAIT_V(8); PG8_WAIT_L(0); PG8_BAR; PG8_MMA(1, 0, At, B0); PG8_MMA(1, 1, At, B1); PG8_BAR; PG8_SCHED;
;             PG8_LDB(B0, 1, 0); PG8_LDB(B1, 1, 1); PG8_SCHED; PG8_LDA(At, 1, 0); PG8_STAGE(PG8_SA(0, 1), a2 + hstepA, voffA);
;             PG8_WAIT_V(8); PG8_WAIT_L(0); PG8_BAR; PG8_MMA(0, 0, At, B0); PG8_MMA(0, 1, At, B1); PG8_BAR; PG8_SCHED;
.LBB0_524:
	ds_read_b128 v[150:153], v161
	ds_read_b128 v[154:157], v161 offset:1024
	ds_read_b128 v[166:169], v161 offset:2048
	ds_read_b128 v[170:173], v161 offset:3072
	ds_read_b128 v[174:177], v162
	ds_read_b128 v[178:181], v162 offset:1024
	ds_read_b128 v[182:185], v162 offset:2048
	ds_read_b128 v[186:189], v162 offset:3072
	s_add_i32 s75, s24, 2
	s_add_u32 s68, s66, 0x100
	s_addc_u32 s69, s67, 0
	s_cmp_eq_u32 s44, s24
	s_cselect_b32 s24, s6, s68
	s_cselect_b32 s25, s7, s69
	s_cselect_b32 s77, s61, s74
	s_cselect_b32 s76, s60, s73
	v_lshl_add_u64 v[158:159], s[66:67], 0, v[140:141]
	s_add_i32 m0, s36, 0xc000
	ds_read_b128 v[190:193], v163
	ds_read_b128 v[194:197], v163 offset:1024
	ds_read_b128 v[198:201], v163 offset:2048
	ds_read_b128 v[202:205], v163 offset:3072
	ds_read_b128 v[206:209], v163 offset:4096
	ds_read_b128 v[210:213], v163 offset:5120
	ds_read_b128 v[214:217], v163 offset:6144
	ds_read_b128 v[218:221], v163 offset:7168
	global_load_lds_dwordx4 v[158:159], off
	v_lshl_add_u64 v[158:159], s[66:67], 0, v[142:143]
	s_add_i32 m0, s36, 0xe000
	s_nop 0
	global_load_lds_dwordx4 v[158:159], off
	s_waitcnt vmcnt(8)
	s_waitcnt lgkmcnt(0)
	s_barrier
	s_setprio 1
	s_waitcnt lgkmcnt(0)
	.p2align 3
	v_mfma_f32_16x16x32_bf16 v[126:129], v[150:153], v[190:193], v[126:129]
	v_mfma_f32_16x16x32_bf16 v[122:125], v[166:169], v[190:193], v[122:125]
	v_mfma_f32_16x16x32_bf16 v[118:121], v[150:153], v[198:201], v[118:121]
	v_mfma_f32_16x16x32_bf16 v[114:117], v[166:169], v[198:201], v[114:117]
	v_mfma_f32_16x16x32_bf16 v[110:113], v[150:153], v[206:209], v[110:113]
	v_mfma_f32_16x16x32_bf16 v[106:109], v[166:169], v[206:209], v[106:109]
	v_mfma_f32_16x16x32_bf16 v[102:105], v[150:153], v[214:217], v[102:105]
	v_mfma_f32_16x16x32_bf16 v[98:101], v[166:169], v[214:217], v[98:101]
	v_mfma_f32_16x16x32_bf16 v[126:129], v[154:157], v[194:197], v[126:129]
	v_mfma_f32_16x16x32_bf16 v[122:125], v[170:173], v[194:197], v[122:125]
	v_mfma_f32_16x16x32_bf16 v[118:121], v[154:157], v[202:205], v[118:121]
	v_mfma_f32_16x16x32_bf16 v[114:117], v[170:173], v[202:205], v[114:117]
	v_mfma_f32_16x16x32_bf16 v[110:113], v[154:157], v[210:213], v[110:113]
	v_mfma_f32_16x16x32_bf16 v[106:109], v[170:173], v[210:213], v[106:109]
	v_mfma_f32_16x16x32_bf16 v[102:105], v[154:157], v[218:221], v[102:105]
	v_mfma_f32_16x16x32_bf16 v[98:101], v[170:173], v[218:221], v[98:101]
	s_setprio 0
	s_setprio 1
	.p2align 3
	v_mfma_f32_16x16x32_bf16 v[62:65], v[174:177], v[190:193], v[62:65]
	v_mfma_f32_16x16x32_bf16 v[58:61], v[182:185], v[190:193], v[58:61]
	v_mfma_f32_16x16x32_bf16 v[54:57], v[174:177], v[198:201], v[54:57]
	v_mfma_f32_16x16x32_bf16 v[50:53], v[182:185], v[198:201], v[50:53]
	v_mfma_f32_16x16x32_bf16 v[46:49], v[174:177], v[206:209], v[46:49]
	v_mfma_f32_16x16x32_bf16 v[42:45], v[182:185], v[206:209], v[42:45]
	v_mfma_f32_16x16x32_bf16 v[38:41], v[174:177], v[214:217], v[38:41]
	v_mfma_f32_16x16x32_bf16 v[34:37], v[182:185], v[214:217], v[34:37]
	v_mfma_f32_16x16x32_bf16 v[62:65], v[178:181], v[194:197], v[62:65]
	v_mfma_f32_16x16x32_bf16 v[58:61], v[186:189], v[194:197], v[58:61]
	v_mfma_f32_16x16x32_bf16 v[54:57], v[178:181], v[202:205], v[54:57]
	v_mfma_f32_16x16x32_bf16 v[50:53], v[186:189], v[202:205], v[50:53]
	v_mfma_f32_16x16x32_bf16 v[46:49], v[178:181], v[210:213], v[46:49]
	v_mfma_f32_16x16x32_bf16 v[42:45], v[186:189], v[210:213], v[42:45]
	v_mfma_f32_16x16x32_bf16 v[38:41], v[178:181], v[218:221], v[38:41]
	v_mfma_f32_16x16x32_bf16 v[34:37], v[186:189], v[218:221], v[34:37]
	s_setprio 0
	s_barrier
	s_add_i32 s66, s45, s21
	v_lshl_add_u64 v[158:159], s[76:77], 0, v[134:135]
	s_mov_b32 m0, s66
	ds_read_b128 v[190:193], v163 offset:16384
	ds_read_b128 v[194:197], v163 offset:17408
	ds_read_b128 v[198:201], v163 offset:18432
	ds_read_b128 v[202:205], v163 offset:19456
	ds_read_b128 v[206:209], v163 offset:20480
	ds_read_b128 v[210:213], v163 offset:21504
	ds_read_b128 v[214:217], v163 offset:22528
	ds_read_b128 v[218:221], v163 offset:23552
	global_load_lds_dwordx4 v[158:159], off
	s_add_i32 m0, s66, 0x2000
	s_add_u32 s66, s76, s8
	v_lshl_add_u64 v[222:223], s[76:77], 0, v[130:131]
	s_addc_u32 s67, s77, s9
	s_add_i32 s76, s46, s21
	global_load_lds_dwordx4 v[222:223], off
	v_lshl_add_u64 v[224:225], s[66:67], 0, v[134:135]
	s_mov_b32 m0, s76
	v_lshl_add_u64 v[226:227], s[66:67], 0, v[130:131]
	global_load_lds_dwordx4 v[224:225], off
	s_add_i32 m0, s76, 0x2000
	v_lshl_add_u64 v[228:229], s[24:25], 0, v[136:137]
	global_load_lds_dwordx4 v[226:227], off
	s_mov_b32 m0, s36
	v_lshl_add_u64 v[230:231], s[24:25], 0, v[132:133]
	global_load_lds_dwordx4 v[228:229], off
	s_mov_b32 m0, s37
	s_nop 0
	global_load_lds_dwordx4 v[230:231], off
	s_waitcnt vmcnt(8)
	s_waitcnt lgkmcnt(0)
	s_barrier
; #define PG8_STAGE(bufoff, gbase, voff) do { _Pragma("unroll") for (int _i = 0; _i < 2; ++_i) \
;         __builtin_amdgcn_global_load_lds((const unsigned*)((const char*)(gbase) + (voff)[_i]), (PG8_LAS unsigned*)(lds + (bufoff) + ldsw + _i * 8192), 16, 0, 0); } while (0)
; #define PG8_LDA(dst, b, h) do { _Pragma("unroll") for (int m = 0; m < 4; ++m) _Pragma("unroll") for (int k = 0; k < 2; ++k) dst[m][k] = *(const PG8_LAS bf16x8*)(lds + PG8_SA(b, h) + aoff + m * 2048 + k * 1024); } while (0)
; #define PG8_LDB(dst, b, h) do { _Pragma("unroll") for (int n = 0; n < 2; ++n) _Pragma("unroll") for (int k = 0; k < 2; ++k) dst[n][k] = *(const PG8_LAS bf16x8*)(lds + PG8_SB(b, h) + boff + n * 2048 + k * 1024); } while (0)
; #define PG8_MMA(ai, bj, At, Bt) do { __builtin_amdgcn_s_setprio(1); _Pragma("unroll") for (int m = 0; m < 4; ++m) _Pragma("unroll") for (int n = 0; n < 2; ++n) _Pragma("unroll") for (int k = 0; k < 2; ++k) \
;         acc[ai][bj][m][n] = __builtin_amdgcn_mfma_f32_16x16x32_bf16(Bt[n][k], At[m][k], acc[ai][bj][m][n], 0, 0, 0); __builtin_amdgcn_s_setprio(0); } while (0)
; #define PG8_WAIT_V(n) asm volatile("s_waitcnt vmcnt(" #n ")" ::: "memory")
; #define PG8_WAIT_L(n) asm volatile("s_waitcnt lgkmcnt(" #n ")" ::: "memory")
; #define PG8_BAR __builtin_amdgcn_s_barrier()
; #define PG8_SCHED __builtin_amdgcn_sched_barrier(0)
; template <class Epi, class Sched, bool ALIGN_EPI = false, bool SP2 = false>
; __device__ __forceinline__ void gemm_phase(PG8_LAS unsigned char* lds, const Gemm g, const Sched& S, const Epi& E) {
;     ...
;             PG8_WAIT_V(8); PG8_WAIT_L(0); PG8_BAR; PG8_MMA(1, 0, At, B0); PG8_MMA(1, 1, At, B1); PG8_BAR; PG8_SCHED;
;             PG8_LDB(B0, 1, 0); PG8_LDB(B1, 1, 1); PG8_SCHED; PG8_LDA(At, 1, 0); PG8_STAGE(PG8_SA(0, 1), a2 + hstepA, voffA);
;             PG8_WAIT_V(8); PG8_WAIT_L(0); PG8_BAR; PG8_MMA(0, 0, At, B0); PG8_MMA(0, 1, At, B1); PG8_BAR; PG8_SCHED;
;             PG8_LDA(At, 1, 1); PG8_STAGE(PG8_SB(1, 0), b3, voffB); PG8_STAGE(PG8_SB(1, 1), b3 + hstepB, voffB); PG8_STAGE(PG8_SA(1, 0), a3, voffA);
	s_setprio 1
	s_waitcnt lgkmcnt(0)
	.p2align 3
	v_mfma_f32_16x16x32_bf16 v[94:97], v[150:153], v[190:193], v[94:97]
	v_mfma_f32_16x16x32_bf16 v[90:93], v[166:169], v[190:193], v[90:93]
	v_mfma_f32_16x16x32_bf16 v[86:89], v[150:153], v[198:201], v[86:89]
	v_mfma_f32_16x16x32_bf16 v[82:85], v[166:169], v[198:201], v[82:85]
	v_mfma_f32_16x16x32_bf16 v[78:81], v[150:153], v[206:209], v[78:81]
	v_mfma_f32_16x16x32_bf16 v[74:77], v[166:169], v[206:209], v[74:77]
	v_mfma_f32_16x16x32_bf16 v[70:73], v[150:153], v[214:217], v[70:73]
	v_mfma_f32_16x16x32_bf16 v[66:69], v[166:169], v[214:217], v[66:69]
	v_mfma_f32_16x16x32_bf16 v[94:97], v[154:157], v[194:197], v[94:97]
	v_mfma_f32_16x16x32_bf16 v[90:93], v[170:173], v[194:197], v[90:93]
	v_mfma_f32_16x16x32_bf16 v[86:89], v[154:157], v[202:205], v[86:89]
	v_mfma_f32_16x16x32_bf16 v[82:85], v[170:173], v[202:205], v[82:85]
	v_mfma_f32_16x16x32_bf16 v[78:81], v[154:157], v[210:213], v[78:81]
	v_mfma_f32_16x16x32_bf16 v[74:77], v[170:173], v[210:213], v[74:77]
	v_mfma_f32_16x16x32_bf16 v[70:73], v[154:157], v[218:221], v[70:73]
	v_mfma_f32_16x16x32_bf16 v[66:69], v[170:173], v[218:221], v[66:69]
	s_setprio 0
	s_setprio 1
	.p2align 3
	v_mfma_f32_16x16x32_bf16 v[30:33], v[174:177], v[190:193], v[30:33]
	v_mfma_f32_16x16x32_bf16 v[26:29], v[182:185], v[190:193], v[26:29]
	v_mfma_f32_16x16x32_bf16 v[22:25], v[174:177], v[198:201], v[22:25]
	v_mfma_f32_16x16x32_bf16 v[18:21], v[182:185], v[198:201], v[18:21]
	v_mfma_f32_16x16x32_bf16 v[14:17], v[174:177], v[206:209], v[14:17]
	v_mfma_f32_16x16x32_bf16 v[10:13], v[182:185], v[206:209], v[10:13]
	v_mfma_f32_16x16x32_bf16 v[6:9], v[174:177], v[214:217], v[6:9]
	v_mfma_f32_16x16x32_bf16 v[2:5], v[182:185], v[214:217], v[2:5]
	v_mfma_f32_16x16x32_bf16 v[30:33], v[178:181], v[194:197], v[30:33]
	v_mfma_f32_16x16x32_bf16 v[26:29], v[186:189], v[194:197], v[26:29]
	v_mfma_f32_16x16x32_bf16 v[22:25], v[178:181], v[202:205], v[22:25]
	v_mfma_f32_16x16x32_bf16 v[18:21], v[186:189], v[202:205], v[18:21]
	v_mfma_f32_16x16x32_bf16 v[14:17], v[178:181], v[210:213], v[14:17]
	v_mfma_f32_16x16x32_bf16 v[10:13], v[186:189], v[210:213], v[10:13]
	v_mfma_f32_16x16x32_bf16 v[6:9], v[178:181], v[218:221], v[6:9]
	v_mfma_f32_16x16x32_bf16 v[2:5], v[186:189], v[218:221], v[2:5]
	s_setprio 0
	s_barrier
	s_add_i32 s66, 0, 0x18000
	v_add_u32_e32 v138, s66, v149
	s_add_i32 s67, 0, 0x1c000
	ds_read_b128 v[150:153], v138
	ds_read_b128 v[154:157], v138 offset:1024
	ds_read_b128 v[166:169], v138 offset:2048
	ds_read_b128 v[170:173], v138 offset:3072
	v_add_u32_e32 v138, s67, v149
	ds_read_b128 v[174:177], v138
	ds_read_b128 v[178:181], v138 offset:1024
	ds_read_b128 v[182:185], v138 offset:2048
	ds_read_b128 v[186:189], v138 offset:3072
	s_add_u32 s24, s24, 0x360000
	s_addc_u32 s25, s25, 0
	s_mov_b32 m0, s38
	v_lshl_add_u64 v[232:233], s[24:25], 0, v[136:137]
	ds_read_b128 v[190:193], v163 offset:32768
	ds_read_b128 v[194:197], v163 offset:33792
	ds_read_b128 v[198:201], v163 offset:34816
	ds_read_b128 v[202:205], v163 offset:35840
	ds_read_b128 v[206:209], v163 offset:36864
	ds_read_b128 v[210:213], v163 offset:37888
	ds_read_b128 v[214:217], v163 offset:38912
	ds_read_b128 v[218:221], v163 offset:39936
	global_load_lds_dwordx4 v[232:233], off
	v_lshl_add_u64 v[232:233], s[24:25], 0, v[132:133]
	s_mov_b32 m0, s39
	s_nop 0
	global_load_lds_dwordx4 v[232:233], off
	s_waitcnt vmcnt(8)
	s_waitcnt lgkmcnt(0)
	s_barrier
	s_setprio 1
	s_waitcnt lgkmcnt(0)
	.p2align 3
	v_mfma_f32_16x16x32_bf16 v[126:129], v[150:153], v[190:193], v[126:129]
	v_mfma_f32_16x16x32_bf16 v[122:125], v[166:169], v[190:193], v[122:125]
	v_mfma_f32_16x16x32_bf16 v[118:121], v[150:153], v[198:201], v[118:121]
	v_mfma_f32_16x16x32_bf16 v[114:117], v[166:169], v[198:201], v[114:117]
	v_mfma_f32_16x16x32_bf16 v[110:113], v[150:153], v[206:209], v[110:113]
	v_mfma_f32_16x16x32_bf16 v[106:109], v[166:169], v[206:209], v[106:109]
	v_mfma_f32_16x16x32_bf16 v[102:105], v[150:153], v[214:217], v[102:105]
	v_mfma_f32_16x16x32_bf16 v[98:101], v[166:169], v[214:217], v[98:101]
	v_mfma_f32_16x16x32_bf16 v[126:129], v[154:157], v[194:197], v[126:129]
	v_mfma_f32_16x16x32_bf16 v[122:125], v[170:173], v[194:197], v[122:125]
	v_mfma_f32_16x16x32_bf16 v[118:121], v[154:157], v[202:205], v[118:121]
	v_mfma_f32_16x16x32_bf16 v[114:117], v[170:173], v[202:205], v[114:117]
	v_mfma_f32_16x16x32_bf16 v[110:113], v[154:157], v[210:213], v[110:113]
	v_mfma_f32_16x16x32_bf16 v[106:109], v[170:173], v[210:213], v[106:109]
	v_mfma_f32_16x16x32_bf16 v[102:105], v[154:157], v[218:221], v[102:105]
	v_mfma_f32_16x16x32_bf16 v[98:101], v[170:173], v[218:221], v[98:101]
	s_setprio 0
	s_setprio 1
	.p2align 3
	v_mfma_f32_16x16x32_bf16 v[62:65], v[174:177], v[190:193], v[62:65]
	v_mfma_f32_16x16x32_bf16 v[58:61], v[182:185], v[190:193], v[58:61]
	v_mfma_f32_16x16x32_bf16 v[54:57], v[174:177], v[198:201], v[54:57]
	v_mfma_f32_16x16x32_bf16 v[50:53], v[182:185], v[198:201], v[50:53]
	v_mfma_f32_16x16x32_bf16 v[46:49], v[174:177], v[206:209], v[46:49]
	v_mfma_f32_16x16x32_bf16 v[42:45], v[182:185], v[206:209], v[42:45]
	v_mfma_f32_16x16x32_bf16 v[38:41], v[174:177], v[214:217], v[38:41]
	v_mfma_f32_16x16x32_bf16 v[34:37], v[182:185], v[214:217], v[34:37]
	v_mfma_f32_16x16x32_bf16 v[62:65], v[178:181], v[194:197], v[62:65]
	v_mfma_f32_16x16x32_bf16 v[58:61], v[186:189], v[194:197], v[58:61]
	v_mfma_f32_16x16x32_bf16 v[54:57], v[178:181], v[202:205], v[54:57]
	v_mfma_f32_16x16x32_bf16 v[50:53], v[186:189], v[202:205], v[50:53]
	v_mfma_f32_16x16x32_bf16 v[46:49], v[178:181], v[210:213], v[46:49]
	v_mfma_f32_16x16x32_bf16 v[42:45], v[186:189], v[210:213], v[42:45]
	v_mfma_f32_16x16x32_bf16 v[38:41], v[178:181], v[218:221], v[38:41]
	v_mfma_f32_16x16x32_bf16 v[34:37], v[186:189], v[218:221], v[34:37]
	s_setprio 0
	s_barrier
; #define PG8_STAGE(bufoff, gbase, voff) do { _Pragma("unroll") for (int _i = 0; _i < 2; ++_i) \
;         __builtin_amdgcn_global_load_lds((const unsigned*)((const char*)(gbase) + (voff)[_i]), (PG8_LAS unsigned*)(lds + (bufoff) + ldsw + _i * 8192), 16, 0, 0); } while (0)
; #define PG8_LDA(dst, b, h) do { _Pragma("unroll") for (int m = 0; m < 4; ++m) _Pragma("unroll") for (int k = 0; k < 2; ++k) dst[m][k] = *(const PG8_LAS bf16x8*)(lds + PG8_SA(b, h) + aoff + m * 2048 + k * 1024); } while (0)
; #define PG8_MMA(ai, bj, At, Bt) do { __builtin_amdgcn_s_setprio(1); _Pragma("unroll") for (int m = 0; m < 4; ++m) _Pragma("unroll") for (int n = 0; n < 2; ++n) _Pragma("unroll") for (int k = 0; k < 2; ++k) \
;         acc[ai][bj][m][n] = __builtin_amdgcn_mfma_f32_16x16x32_bf16(Bt[n][k], At[m][k], acc[ai][bj][m][n], 0, 0, 0); __builtin_amdgcn_s_setprio(0); } while (0)
; #define PG8_WAIT_V(n) asm volatile("s_waitcnt vmcnt(" #n ")" ::: "memory")
; #define PG8_WAIT_L(n) asm volatile("s_waitcnt lgkmcnt(" #n ")" ::: "memory")
; #define PG8_BAR __builtin_amdgcn_s_barrier()
; #define PG8_SCHED __builtin_amdgcn_sched_barrier(0)
; template <class Epi, class Sched, bool ALIGN_EPI = false, bool SP2 = false>
; __device__ __forceinline__ void gemm_phase(PG8_LAS unsigned char* lds, const Gemm g, const Sched& S, const Epi& E) {
;     ...
;             PG8_LDA(At, 1, 1); PG8_STAGE(PG8_SB(1, 0), b3, voffB); PG8_STAGE(PG8_SB(1, 1), b3 + hstepB, voffB); PG8_STAGE(PG8_SA(1, 0), a3, voffA);
;             PG8_WAIT_V(8); PG8_WAIT_L(0); PG8_BAR; PG8_MMA(1, 0, At, B0); PG8_MMA(1, 1, At, B1); PG8_BAR; PG8_SCHED;
	s_add_i32 s24, s66, s21
	v_lshl_add_u64 v[158:159], v[158:159], 0, s[14:15]
	s_mov_b32 m0, s24
	ds_read_b128 v[190:193], v163 offset:49152
	ds_read_b128 v[194:197], v163 offset:50176
	ds_read_b128 v[198:201], v163 offset:51200
	ds_read_b128 v[202:205], v163 offset:52224
	ds_read_b128 v[206:209], v163 offset:53248
	ds_read_b128 v[210:213], v163 offset:54272
	ds_read_b128 v[214:217], v163 offset:55296
	ds_read_b128 v[218:221], v163 offset:56320
	global_load_lds_dwordx4 v[158:159], off
	v_lshl_add_u64 v[158:159], v[222:223], 0, s[14:15]
	s_add_i32 m0, s24, 0x2000
	s_add_i32 s24, s67, s21
	global_load_lds_dwordx4 v[158:159], off
	v_lshl_add_u64 v[158:159], v[224:225], 0, s[14:15]
	s_mov_b32 m0, s24
	s_nop 0
	global_load_lds_dwordx4 v[158:159], off
	v_lshl_add_u64 v[158:159], v[226:227], 0, s[14:15]
	s_add_i32 m0, s24, 0x2000
	s_nop 0
	global_load_lds_dwordx4 v[158:159], off
	v_lshl_add_u64 v[158:159], v[228:229], 0, s[14:15]
	s_mov_b32 m0, s42
	s_nop 0
	global_load_lds_dwordx4 v[158:159], off
	v_lshl_add_u64 v[158:159], v[230:231], 0, s[14:15]
	s_mov_b32 m0, s43
	s_nop 0
	global_load_lds_dwordx4 v[158:159], off
	s_waitcnt vmcnt(8)
	s_waitcnt lgkmcnt(0)
	s_barrier
	s_setprio 1
	s_waitcnt lgkmcnt(0)
	.p2align 3
	v_mfma_f32_16x16x32_bf16 v[94:97], v[150:153], v[190:193], v[94:97]
	v_mfma_f32_16x16x32_bf16 v[90:93], v[166:169], v[190:193], v[90:93]
	v_mfma_f32_16x16x32_bf16 v[86:89], v[150:153], v[198:201], v[86:89]
	v_mfma_f32_16x16x32_bf16 v[82:85], v[166:169], v[198:201], v[82:85]
	v_mfma_f32_16x16x32_bf16 v[78:81], v[150:153], v[206:209], v[78:81]
	v_mfma_f32_16x16x32_bf16 v[74:77], v[166:169], v[206:209], v[74:77]
	v_mfma_f32_16x16x32_bf16 v[70:73], v[150:153], v[214:217], v[70:73]
	v_mfma_f32_16x16x32_bf16 v[66:69], v[166:169], v[214:217], v[66:69]
	v_mfma_f32_16x16x32_bf16 v[94:97], v[154:157], v[194:197], v[94:97]
	v_mfma_f32_16x16x32_bf16 v[90:93], v[170:173], v[194:197], v[90:93]
	v_mfma_f32_16x16x32_bf16 v[86:89], v[154:157], v[202:205], v[86:89]
	v_mfma_f32_16x16x32_bf16 v[82:85], v[170:173], v[202:205], v[82:85]
	v_mfma_f32_16x16x32_bf16 v[78:81], v[154:157], v[210:213], v[78:81]
	v_mfma_f32_16x16x32_bf16 v[74:77], v[170:173], v[210:213], v[74:77]
	v_mfma_f32_16x16x32_bf16 v[70:73], v[154:157], v[218:221], v[70:73]
	v_mfma_f32_16x16x32_bf16 v[66:69], v[170:173], v[218:221], v[66:69]
	s_setprio 0
	s_setprio 1
	.p2align 3
	v_mfma_f32_16x16x32_bf16 v[30:33], v[174:177], v[190:193], v[30:33]
	v_mfma_f32_16x16x32_bf16 v[26:29], v[182:185], v[190:193], v[26:29]
	v_mfma_f32_16x16x32_bf16 v[22:25], v[174:177], v[198:201], v[22:25]
	v_mfma_f32_16x16x32_bf16 v[18:21], v[182:185], v[198:201], v[18:21]
	v_mfma_f32_16x16x32_bf16 v[14:17], v[174:177], v[206:209], v[14:17]
	v_mfma_f32_16x16x32_bf16 v[10:13], v[182:185], v[206:209], v[10:13]
	v_mfma_f32_16x16x32_bf16 v[6:9], v[174:177], v[214:217], v[6:9]
	v_mfma_f32_16x16x32_bf16 v[2:5], v[182:185], v[214:217], v[2:5]
	v_mfma_f32_16x16x32_bf16 v[30:33], v[178:181], v[194:197], v[30:33]
	v_mfma_f32_16x16x32_bf16 v[26:29], v[186:189], v[194:197], v[26:29]
	v_mfma_f32_16x16x32_bf16 v[22:25], v[178:181], v[202:205], v[22:25]
	v_mfma_f32_16x16x32_bf16 v[18:21], v[186:189], v[202:205], v[18:21]
	v_mfma_f32_16x16x32_bf16 v[14:17], v[178:181], v[210:213], v[14:17]
	v_mfma_f32_16x16x32_bf16 v[10:13], v[186:189], v[210:213], v[10:13]
	v_mfma_f32_16x16x32_bf16 v[6:9], v[178:181], v[218:221], v[6:9]
	v_mfma_f32_16x16x32_bf16 v[2:5], v[186:189], v[218:221], v[2:5]
	s_setprio 0
	s_barrier
	s_add_u32 s73, s73, 0x100
	s_addc_u32 s74, s74, 0
	s_cmp_ge_i32 s75, s41
	s_mov_b64 s[66:67], s[68:69]
	s_mov_b32 s24, s75
	s_cbranch_scc0 .LBB0_524

; #define PG8_STAGE(bufoff, gbase, voff) do { _Pragma("unroll") for (int _i = 0; _i < 2; ++_i) \
;         __builtin_amdgcn_global_load_lds((const unsigned*)((const char*)(gbase) + (voff)[_i]), (PG8_LAS unsigned*)(lds + (bufoff) + ldsw + _i * 8192), 16, 0, 0); } while (0)
; #define PG8_LDA(dst, b, h) do { _Pragma("unroll") for (int m = 0; m < 4; ++m) _Pragma("unroll") for (int k = 0; k < 2; ++k) dst[m][k] = *(const PG8_LAS bf16x8*)(lds + PG8_SA(b, h) + aoff + m * 2048 + k * 1024); } while (0)
; #define PG8_LDB(dst, b, h) do { _Pragma("unroll") for (int n = 0; n < 2; ++n) _Pragma("unroll") for (int k = 0; k < 2; ++k) dst[n][k] = *(const PG8_LAS bf16x8*)(lds + PG8_SB(b, h) + boff + n * 2048 + k * 1024); } while (0)
; #define PG8_MMA(ai, bj, At, Bt) do { __builtin_amdgcn_s_setprio(1); _Pragma("unroll") for (int m = 0; m < 4; ++m) _Pragma("unroll") for (int n = 0; n < 2; ++n) _Pragma("unroll") for (int k = 0; k < 2; ++k) \
;         acc[ai][bj][m][n] = __builtin_amdgcn_mfma_f32_16x16x32_bf16(Bt[n][k], At[m][k], acc[ai][bj][m][n], 0, 0, 0); __builtin_amdgcn_s_setprio(0); } while (0)
; #define PG8_WAIT_V(n) asm volatile("s_waitcnt vmcnt(" #n ")" ::: "memory")
; #define PG8_WAIT_L(n) asm volatile("s_waitcnt lgkmcnt(" #n ")" ::: "memory")
; #define PG8_BAR __builtin_amdgcn_s_barrier()
; #define PG8_SCHED __builtin_amdgcn_sched_barrier(0)
; template <class Epi, class Sched, bool ALIGN_EPI = false, bool SP2 = false>
; __device__ __forceinline__ void gemm_phase(PG8_LAS unsigned char* lds, const Gemm g, const Sched& S, const Epi& E) {
;     ...
;             PG8_LDB(B0, 0, 0); PG8_LDB(B1, 0, 1); PG8_SCHED; PG8_LDA(At, 0, 0); PG8_STAGE(PG8_SA(1, 1), a1 + hstepA, voffA);
;             PG8_WAIT_V(8); PG8_WAIT_L(0); PG8_BAR; PG8_MMA(0, 0, At, B0); PG8_MMA(0, 1, At, B1); PG8_BAR; PG8_SCHED;
;             PG8_LDA(At, 0, 1); PG8_STAGE(PG8_SB(0, 0), b2, voffB); PG8_STAGE(PG8_SB(0, 1), b2 + hstepB, voffB); PG8_STAGE(PG8_SA(0, 0), a2, voffA);
;             PG8_WAIT_V(8); PG8_WAIT_L(0); PG8_BAR; PG8_MMA(1, 0, At, B0); PG8_MMA(1, 1, At, B1); PG8_BAR; PG8_SCHED;
.Lsp_LBB0_839:
.LBB0_839:
	ds_read_b128 v[130:133], v166
	ds_read_b128 v[134:137], v166 offset:1024
	ds_read_b128 v[138:141], v166 offset:2048
	ds_read_b128 v[142:145], v166 offset:3072
	ds_read_b128 v[170:173], v167
	ds_read_b128 v[174:177], v167 offset:1024
	ds_read_b128 v[178:181], v167 offset:2048
	ds_read_b128 v[182:185], v167 offset:3072
	s_add_u32 s24, s36, 0xfff00080
	s_addc_u32 s25, s37, -1
	s_cmp_eq_u32 s69, 60
	s_cselect_b32 s25, s17, s25
	s_cselect_b32 s24, s49, s24
	s_cselect_b32 s39, s15, s68
	s_cselect_b32 s38, s62, s63
	s_add_i32 m0, s23, 0xc000
	ds_read_b128 v[186:189], v168
	ds_read_b128 v[190:193], v168 offset:1024
	ds_read_b128 v[194:197], v168 offset:2048
	ds_read_b128 v[198:201], v168 offset:3072
	ds_read_b128 v[202:205], v168 offset:4096
	ds_read_b128 v[206:209], v168 offset:5120
	ds_read_b128 v[210:213], v168 offset:6144
	ds_read_b128 v[214:217], v168 offset:7168
	global_load_lds_dwordx4 v154, s[36:37]
	s_add_i32 m0, s23, 0xe000
	s_nop 0
	global_load_lds_dwordx4 v156, s[36:37]
	s_waitcnt vmcnt(8)
	s_waitcnt lgkmcnt(0)
	s_barrier
	s_waitcnt lgkmcnt(0)
	.p2align 3
	v_mfma_f32_16x16x32_bf16 v[126:129], v[130:133], v[186:189], v[126:129]
	v_mfma_f32_16x16x32_bf16 v[122:125], v[138:141], v[186:189], v[122:125]
	v_mfma_f32_16x16x32_bf16 v[118:121], v[130:133], v[194:197], v[118:121]
	v_mfma_f32_16x16x32_bf16 v[114:117], v[138:141], v[194:197], v[114:117]
	v_mfma_f32_16x16x32_bf16 v[110:113], v[130:133], v[202:205], v[110:113]
	v_mfma_f32_16x16x32_bf16 v[102:105], v[138:141], v[202:205], v[102:105]
	v_mfma_f32_16x16x32_bf16 v[94:97], v[130:133], v[210:213], v[94:97]
	v_mfma_f32_16x16x32_bf16 v[86:89], v[138:141], v[210:213], v[86:89]
	v_mfma_f32_16x16x32_bf16 v[126:129], v[134:137], v[190:193], v[126:129]
	v_mfma_f32_16x16x32_bf16 v[122:125], v[142:145], v[190:193], v[122:125]
	v_mfma_f32_16x16x32_bf16 v[118:121], v[134:137], v[198:201], v[118:121]
	v_mfma_f32_16x16x32_bf16 v[114:117], v[142:145], v[198:201], v[114:117]
	v_mfma_f32_16x16x32_bf16 v[110:113], v[134:137], v[206:209], v[110:113]
	v_mfma_f32_16x16x32_bf16 v[102:105], v[142:145], v[206:209], v[102:105]
	v_mfma_f32_16x16x32_bf16 v[94:97], v[134:137], v[214:217], v[94:97]
	v_mfma_f32_16x16x32_bf16 v[86:89], v[142:145], v[214:217], v[86:89]
	v_mfma_f32_16x16x32_bf16 v[106:109], v[170:173], v[186:189], v[106:109]
	v_mfma_f32_16x16x32_bf16 v[98:101], v[178:181], v[186:189], v[98:101]
	v_mfma_f32_16x16x32_bf16 v[90:93], v[170:173], v[194:197], v[90:93]
	v_mfma_f32_16x16x32_bf16 v[82:85], v[178:181], v[194:197], v[82:85]
	v_mfma_f32_16x16x32_bf16 v[78:81], v[170:173], v[202:205], v[78:81]
	v_mfma_f32_16x16x32_bf16 v[74:77], v[178:181], v[202:205], v[74:77]
	v_mfma_f32_16x16x32_bf16 v[70:73], v[170:173], v[210:213], v[70:73]
	v_mfma_f32_16x16x32_bf16 v[66:69], v[178:181], v[210:213], v[66:69]
	v_mfma_f32_16x16x32_bf16 v[106:109], v[174:177], v[190:193], v[106:109]
	v_mfma_f32_16x16x32_bf16 v[98:101], v[182:185], v[190:193], v[98:101]
	v_mfma_f32_16x16x32_bf16 v[90:93], v[174:177], v[198:201], v[90:93]
	v_mfma_f32_16x16x32_bf16 v[82:85], v[182:185], v[198:201], v[82:85]
	v_mfma_f32_16x16x32_bf16 v[78:81], v[174:177], v[206:209], v[78:81]
	v_mfma_f32_16x16x32_bf16 v[74:77], v[182:185], v[206:209], v[74:77]
	v_mfma_f32_16x16x32_bf16 v[70:73], v[174:177], v[214:217], v[70:73]
	v_mfma_f32_16x16x32_bf16 v[66:69], v[182:185], v[214:217], v[66:69]
	s_barrier
	s_add_i32 s72, s45, s26
	s_add_u32 s98, s38, 0x80
	s_addc_u32 s99, s39, 0
	s_add_u32 s100, s24, 0x80
	s_addc_u32 s101, s25, 0
	s_mov_b32 m0, s72
	ds_read_b128 v[186:189], v168 offset:16384
	ds_read_b128 v[190:193], v168 offset:17408
	ds_read_b128 v[194:197], v168 offset:18432
	ds_read_b128 v[198:201], v168 offset:19456
	ds_read_b128 v[202:205], v168 offset:20480
	ds_read_b128 v[206:209], v168 offset:21504
	ds_read_b128 v[210:213], v168 offset:22528
	ds_read_b128 v[214:217], v168 offset:23552
	global_load_lds_dwordx4 v150, s[38:39]
	s_add_i32 m0, s72, 0x2000
	s_add_u32 s72, s38, 0x100000
	s_addc_u32 s73, s39, 0
	s_add_i32 s74, s46, s26
	global_load_lds_dwordx4 v146, s[38:39]
	s_mov_b32 m0, s74
	s_nop 0
	global_load_lds_dwordx4 v150, s[72:73]
	s_add_i32 m0, s74, 0x2000
	s_nop 0
	global_load_lds_dwordx4 v146, s[72:73]
	s_mov_b32 m0, s23
	s_nop 0
	global_load_lds_dwordx4 v152, s[24:25]
	s_mov_b32 m0, s27
	s_nop 0
	global_load_lds_dwordx4 v148, s[24:25]
	s_waitcnt vmcnt(8)
	s_waitcnt lgkmcnt(0)
	s_barrier
	s_waitcnt lgkmcnt(0)
	.p2align 3
	v_mfma_f32_16x16x32_bf16 v[62:65], v[130:133], v[186:189], v[62:65]
	v_mfma_f32_16x16x32_bf16 v[58:61], v[138:141], v[186:189], v[58:61]
	v_mfma_f32_16x16x32_bf16 v[50:53], v[130:133], v[194:197], v[50:53]
	v_mfma_f32_16x16x32_bf16 v[42:45], v[138:141], v[194:197], v[42:45]
	v_mfma_f32_16x16x32_bf16 v[34:37], v[130:133], v[202:205], v[34:37]
	v_mfma_f32_16x16x32_bf16 v[26:29], v[138:141], v[202:205], v[26:29]
	v_mfma_f32_16x16x32_bf16 v[18:21], v[130:133], v[210:213], v[18:21]
	v_mfma_f32_16x16x32_bf16 v[10:13], v[138:141], v[210:213], v[10:13]
	v_mfma_f32_16x16x32_bf16 v[62:65], v[134:137], v[190:193], v[62:65]
	v_mfma_f32_16x16x32_bf16 v[58:61], v[142:145], v[190:193], v[58:61]
	v_mfma_f32_16x16x32_bf16 v[50:53], v[134:137], v[198:201], v[50:53]
	v_mfma_f32_16x16x32_bf16 v[42:45], v[142:145], v[198:201], v[42:45]
	v_mfma_f32_16x16x32_bf16 v[34:37], v[134:137], v[206:209], v[34:37]
	v_mfma_f32_16x16x32_bf16 v[26:29], v[142:145], v[206:209], v[26:29]
	v_mfma_f32_16x16x32_bf16 v[18:21], v[134:137], v[214:217], v[18:21]
	v_mfma_f32_16x16x32_bf16 v[10:13], v[142:145], v[214:217], v[10:13]
	v_mfma_f32_16x16x32_bf16 v[54:57], v[170:173], v[186:189], v[54:57]
	v_mfma_f32_16x16x32_bf16 v[46:49], v[178:181], v[186:189], v[46:49]
	v_mfma_f32_16x16x32_bf16 v[38:41], v[170:173], v[194:197], v[38:41]
	v_mfma_f32_16x16x32_bf16 v[30:33], v[178:181], v[194:197], v[30:33]
	v_mfma_f32_16x16x32_bf16 v[22:25], v[170:173], v[202:205], v[22:25]
	v_mfma_f32_16x16x32_bf16 v[14:17], v[178:181], v[202:205], v[14:17]
	v_mfma_f32_16x16x32_bf16 v[6:9], v[170:173], v[210:213], v[6:9]
	v_mfma_f32_16x16x32_bf16 v[2:5], v[178:181], v[210:213], v[2:5]
	v_mfma_f32_16x16x32_bf16 v[54:57], v[174:177], v[190:193], v[54:57]
	v_mfma_f32_16x16x32_bf16 v[46:49], v[182:185], v[190:193], v[46:49]
	v_mfma_f32_16x16x32_bf16 v[38:41], v[174:177], v[198:201], v[38:41]
	v_mfma_f32_16x16x32_bf16 v[30:33], v[182:185], v[198:201], v[30:33]
	v_mfma_f32_16x16x32_bf16 v[22:25], v[174:177], v[206:209], v[22:25]
	v_mfma_f32_16x16x32_bf16 v[14:17], v[182:185], v[206:209], v[14:17]
	v_mfma_f32_16x16x32_bf16 v[6:9], v[174:177], v[214:217], v[6:9]
	v_mfma_f32_16x16x32_bf16 v[2:5], v[182:185], v[214:217], v[2:5]
	s_barrier
; #define PG8_STAGE(bufoff, gbase, voff) do { _Pragma("unroll") for (int _i = 0; _i < 2; ++_i) \
;         __builtin_amdgcn_global_load_lds((const unsigned*)((const char*)(gbase) + (voff)[_i]), (PG8_LAS unsigned*)(lds + (bufoff) + ldsw + _i * 8192), 16, 0, 0); } while (0)
; #define PG8_LDA(dst, b, h) do { _Pragma("unroll") for (int m = 0; m < 4; ++m) _Pragma("unroll") for (int k = 0; k < 2; ++k) dst[m][k] = *(const PG8_LAS bf16x8*)(lds + PG8_SA(b, h) + aoff + m * 2048 + k * 1024); } while (0)
; #define PG8_LDB(dst, b, h) do { _Pragma("unroll") for (int n = 0; n < 2; ++n) _Pragma("unroll") for (int k = 0; k < 2; ++k) dst[n][k] = *(const PG8_LAS bf16x8*)(lds + PG8_SB(b, h) + boff + n * 2048 + k * 1024); } while (0)
; #define PG8_MMA(ai, bj, At, Bt) do { __builtin_amdgcn_s_setprio(1); _Pragma("unroll") for (int m = 0; m < 4; ++m) _Pragma("unroll") for (int n = 0; n < 2; ++n) _Pragma("unroll") for (int k = 0; k < 2; ++k) \
;         acc[ai][bj][m][n] = __builtin_amdgcn_mfma_f32_16x16x32_bf16(Bt[n][k], At[m][k], acc[ai][bj][m][n], 0, 0, 0); __builtin_amdgcn_s_setprio(0); } while (0)
; #define PG8_WAIT_V(n) asm volatile("s_waitcnt vmcnt(" #n ")" ::: "memory")
; #define PG8_WAIT_L(n) asm volatile("s_waitcnt lgkmcnt(" #n ")" ::: "memory")
; #define PG8_BAR __builtin_amdgcn_s_barrier()
; #define PG8_SCHED __builtin_amdgcn_sched_barrier(0)
; template <class Epi, class Sched, bool ALIGN_EPI = false, bool SP2 = false>
; __device__ __forceinline__ void gemm_phase(PG8_LAS unsigned char* lds, const Gemm g, const Sched& S, const Epi& E) {
;     ...
;             PG8_LDB(B0, 1, 0); PG8_LDB(B1, 1, 1); PG8_SCHED; PG8_LDA(At, 1, 0); PG8_STAGE(PG8_SA(0, 1), a2 + hstepA, voffA);
;             PG8_WAIT_V(8); PG8_WAIT_L(0); PG8_BAR; PG8_MMA(0, 0, At, B0); PG8_MMA(0, 1, At, B1); PG8_BAR; PG8_SCHED;
;             PG8_LDA(At, 1, 1); PG8_STAGE(PG8_SB(1, 0), b3, voffB); PG8_STAGE(PG8_SB(1, 1), b3 + hstepB, voffB); PG8_STAGE(PG8_SA(1, 0), a3, voffA);
;             PG8_WAIT_V(8); PG8_WAIT_L(0); PG8_BAR; PG8_MMA(1, 0, At, B0); PG8_MMA(1, 1, At, B1); PG8_BAR; PG8_SCHED;
	s_add_i32 s72, 0, 0x18000
	s_add_i32 s73, 0, 0x1c000
	v_add_u32_e32 v142, s72, v164
	v_add_u32_e32 v169, s73, v164
	ds_read_b128 v[130:133], v142
	ds_read_b128 v[134:137], v142 offset:1024
	ds_read_b128 v[138:141], v142 offset:2048
	ds_read_b128 v[142:145], v142 offset:3072
	ds_read_b128 v[170:173], v169
	ds_read_b128 v[174:177], v169 offset:1024
	ds_read_b128 v[178:181], v169 offset:2048
	ds_read_b128 v[182:185], v169 offset:3072
	s_add_u32 s24, s24, 0x100000
	s_addc_u32 s25, s25, 0
	s_mov_b32 m0, s34
	ds_read_b128 v[186:189], v168 offset:32768
	ds_read_b128 v[190:193], v168 offset:33792
	ds_read_b128 v[194:197], v168 offset:34816
	ds_read_b128 v[198:201], v168 offset:35840
	ds_read_b128 v[202:205], v168 offset:36864
	ds_read_b128 v[206:209], v168 offset:37888
	ds_read_b128 v[210:213], v168 offset:38912
	ds_read_b128 v[214:217], v168 offset:39936
	global_load_lds_dwordx4 v152, s[24:25]
	s_mov_b32 m0, s35
	s_nop 0
	global_load_lds_dwordx4 v148, s[24:25]
	s_waitcnt vmcnt(8)
	s_waitcnt lgkmcnt(0)
	s_barrier
	s_waitcnt lgkmcnt(0)
	.p2align 3
	v_mfma_f32_16x16x32_bf16 v[126:129], v[130:133], v[186:189], v[126:129]
	v_mfma_f32_16x16x32_bf16 v[122:125], v[138:141], v[186:189], v[122:125]
	v_mfma_f32_16x16x32_bf16 v[118:121], v[130:133], v[194:197], v[118:121]
	v_mfma_f32_16x16x32_bf16 v[114:117], v[138:141], v[194:197], v[114:117]
	v_mfma_f32_16x16x32_bf16 v[110:113], v[130:133], v[202:205], v[110:113]
	v_mfma_f32_16x16x32_bf16 v[102:105], v[138:141], v[202:205], v[102:105]
	v_mfma_f32_16x16x32_bf16 v[94:97], v[130:133], v[210:213], v[94:97]
	v_mfma_f32_16x16x32_bf16 v[86:89], v[138:141], v[210:213], v[86:89]
	v_mfma_f32_16x16x32_bf16 v[126:129], v[134:137], v[190:193], v[126:129]
	v_mfma_f32_16x16x32_bf16 v[122:125], v[142:145], v[190:193], v[122:125]
	v_mfma_f32_16x16x32_bf16 v[118:121], v[134:137], v[198:201], v[118:121]
	v_mfma_f32_16x16x32_bf16 v[114:117], v[142:145], v[198:201], v[114:117]
	v_mfma_f32_16x16x32_bf16 v[110:113], v[134:137], v[206:209], v[110:113]
	v_mfma_f32_16x16x32_bf16 v[102:105], v[142:145], v[206:209], v[102:105]
	v_mfma_f32_16x16x32_bf16 v[94:97], v[134:137], v[214:217], v[94:97]
	v_mfma_f32_16x16x32_bf16 v[86:89], v[142:145], v[214:217], v[86:89]
	v_mfma_f32_16x16x32_bf16 v[106:109], v[170:173], v[186:189], v[106:109]
	v_mfma_f32_16x16x32_bf16 v[98:101], v[178:181], v[186:189], v[98:101]
	v_mfma_f32_16x16x32_bf16 v[90:93], v[170:173], v[194:197], v[90:93]
	v_mfma_f32_16x16x32_bf16 v[82:85], v[178:181], v[194:197], v[82:85]
	v_mfma_f32_16x16x32_bf16 v[78:81], v[170:173], v[202:205], v[78:81]
	v_mfma_f32_16x16x32_bf16 v[74:77], v[178:181], v[202:205], v[74:77]
	v_mfma_f32_16x16x32_bf16 v[70:73], v[170:173], v[210:213], v[70:73]
	v_mfma_f32_16x16x32_bf16 v[66:69], v[178:181], v[210:213], v[66:69]
	v_mfma_f32_16x16x32_bf16 v[106:109], v[174:177], v[190:193], v[106:109]
	v_mfma_f32_16x16x32_bf16 v[98:101], v[182:185], v[190:193], v[98:101]
	v_mfma_f32_16x16x32_bf16 v[90:93], v[174:177], v[198:201], v[90:93]
	v_mfma_f32_16x16x32_bf16 v[82:85], v[182:185], v[198:201], v[82:85]
	v_mfma_f32_16x16x32_bf16 v[78:81], v[174:177], v[206:209], v[78:81]
	v_mfma_f32_16x16x32_bf16 v[74:77], v[182:185], v[206:209], v[74:77]
	v_mfma_f32_16x16x32_bf16 v[70:73], v[174:177], v[214:217], v[70:73]
	v_mfma_f32_16x16x32_bf16 v[66:69], v[182:185], v[214:217], v[66:69]
	s_barrier
	s_add_i32 s24, s72, s26
	s_mov_b32 m0, s24
	ds_read_b128 v[186:189], v168 offset:49152
	ds_read_b128 v[190:193], v168 offset:50176
	ds_read_b128 v[194:197], v168 offset:51200
	ds_read_b128 v[198:201], v168 offset:52224
	ds_read_b128 v[202:205], v168 offset:53248
	ds_read_b128 v[206:209], v168 offset:54272
	ds_read_b128 v[210:213], v168 offset:55296
	ds_read_b128 v[214:217], v168 offset:56320
	global_load_lds_dwordx4 v150, s[98:99]
	s_add_i32 m0, s24, 0x2000
	s_add_u32 s24, s38, 0x100080
	s_addc_u32 s25, s39, 0
	s_add_i32 s38, s73, s26
	global_load_lds_dwordx4 v146, s[98:99]
	s_mov_b32 m0, s38
	s_nop 0
	global_load_lds_dwordx4 v150, s[24:25]
	s_add_i32 m0, s38, 0x2000
	s_nop 0
	global_load_lds_dwordx4 v146, s[24:25]
	s_mov_b32 m0, s43
	s_nop 0
	global_load_lds_dwordx4 v152, s[100:101]
	s_mov_b32 m0, s44
	s_nop 0
	global_load_lds_dwordx4 v148, s[100:101]
	s_waitcnt vmcnt(8)
	s_waitcnt lgkmcnt(0)
	s_barrier
	s_waitcnt lgkmcnt(0)
	.p2align 3
	v_mfma_f32_16x16x32_bf16 v[62:65], v[130:133], v[186:189], v[62:65]
	v_mfma_f32_16x16x32_bf16 v[58:61], v[138:141], v[186:189], v[58:61]
	v_mfma_f32_16x16x32_bf16 v[50:53], v[130:133], v[194:197], v[50:53]
	v_mfma_f32_16x16x32_bf16 v[42:45], v[138:141], v[194:197], v[42:45]
	v_mfma_f32_16x16x32_bf16 v[34:37], v[130:133], v[202:205], v[34:37]
	v_mfma_f32_16x16x32_bf16 v[26:29], v[138:141], v[202:205], v[26:29]
	v_mfma_f32_16x16x32_bf16 v[18:21], v[130:133], v[210:213], v[18:21]
	v_mfma_f32_16x16x32_bf16 v[10:13], v[138:141], v[210:213], v[10:13]
	v_mfma_f32_16x16x32_bf16 v[62:65], v[134:137], v[190:193], v[62:65]
	v_mfma_f32_16x16x32_bf16 v[58:61], v[142:145], v[190:193], v[58:61]
	v_mfma_f32_16x16x32_bf16 v[50:53], v[134:137], v[198:201], v[50:53]
	v_mfma_f32_16x16x32_bf16 v[42:45], v[142:145], v[198:201], v[42:45]
	v_mfma_f32_16x16x32_bf16 v[34:37], v[134:137], v[206:209], v[34:37]
	v_mfma_f32_16x16x32_bf16 v[26:29], v[142:145], v[206:209], v[26:29]
	v_mfma_f32_16x16x32_bf16 v[18:21], v[134:137], v[214:217], v[18:21]
	v_mfma_f32_16x16x32_bf16 v[10:13], v[142:145], v[214:217], v[10:13]
	v_mfma_f32_16x16x32_bf16 v[54:57], v[170:173], v[186:189], v[54:57]
	v_mfma_f32_16x16x32_bf16 v[46:49], v[178:181], v[186:189], v[46:49]
	v_mfma_f32_16x16x32_bf16 v[38:41], v[170:173], v[194:197], v[38:41]
	v_mfma_f32_16x16x32_bf16 v[30:33], v[178:181], v[194:197], v[30:33]
	v_mfma_f32_16x16x32_bf16 v[22:25], v[170:173], v[202:205], v[22:25]
	v_mfma_f32_16x16x32_bf16 v[14:17], v[178:181], v[202:205], v[14:17]
	v_mfma_f32_16x16x32_bf16 v[6:9], v[170:173], v[210:213], v[6:9]
	v_mfma_f32_16x16x32_bf16 v[2:5], v[178:181], v[210:213], v[2:5]
	v_mfma_f32_16x16x32_bf16 v[54:57], v[174:177], v[190:193], v[54:57]
	v_mfma_f32_16x16x32_bf16 v[46:49], v[182:185], v[190:193], v[46:49]
	v_mfma_f32_16x16x32_bf16 v[38:41], v[174:177], v[198:201], v[38:41]
	v_mfma_f32_16x16x32_bf16 v[30:33], v[182:185], v[198:201], v[30:33]
	v_mfma_f32_16x16x32_bf16 v[22:25], v[174:177], v[206:209], v[22:25]
	v_mfma_f32_16x16x32_bf16 v[14:17], v[182:185], v[206:209], v[14:17]
	v_mfma_f32_16x16x32_bf16 v[6:9], v[174:177], v[214:217], v[6:9]
	v_mfma_f32_16x16x32_bf16 v[2:5], v[182:185], v[214:217], v[2:5]
	s_barrier
	s_add_i32 s69, s69, 2
	s_add_u32 s36, s36, 0x100
	s_addc_u32 s37, s37, 0
	s_add_u32 s63, s63, 0x100
	s_addc_u32 s68, s68, 0
	s_cmp_gt_u32 s69, 61
	s_cbranch_scc0 .LBB0_839
	s_setprio 0
	s_and_b64 vcc, exec, s[10:11]
	s_cbranch_vccz .LBB0_842
	s_barrier

; #define PG8_STAGE(bufoff, gbase, voff) do { _Pragma("unroll") for (int _i = 0; _i < 2; ++_i) \
;         __builtin_amdgcn_global_load_lds((const unsigned*)((const char*)(gbase) + (voff)[_i]), (PG8_LAS unsigned*)(lds + (bufoff) + ldsw + _i * 8192), 16, 0, 0); } while (0)
; #define PG8_LDA(dst, b, h) do { _Pragma("unroll") for (int m = 0; m < 4; ++m) _Pragma("unroll") for (int k = 0; k < 2; ++k) dst[m][k] = *(const PG8_LAS bf16x8*)(lds + PG8_SA(b, h) + aoff + m * 2048 + k * 1024); } while (0)
; #define PG8_LDB(dst, b, h) do { _Pragma("unroll") for (int n = 0; n < 2; ++n) _Pragma("unroll") for (int k = 0; k < 2; ++k) dst[n][k] = *(const PG8_LAS bf16x8*)(lds + PG8_SB(b, h) + boff + n * 2048 + k * 1024); } while (0)
; #define PG8_MMA(ai, bj, At, Bt) do { __builtin_amdgcn_s_setprio(1); _Pragma("unroll") for (int m = 0; m < 4; ++m) _Pragma("unroll") for (int n = 0; n < 2; ++n) _Pragma("unroll") for (int k = 0; k < 2; ++k) \
;         acc[ai][bj][m][n] = __builtin_amdgcn_mfma_f32_16x16x32_bf16(Bt[n][k], At[m][k], acc[ai][bj][m][n], 0, 0, 0); __builtin_amdgcn_s_setprio(0); } while (0)
; #define PG8_WAIT_V(n) asm volatile("s_waitcnt vmcnt(" #n ")" ::: "memory")
; #define PG8_WAIT_L(n) asm volatile("s_waitcnt lgkmcnt(" #n ")" ::: "memory")
; #define PG8_BAR __builtin_amdgcn_s_barrier()
; #define PG8_SCHED __builtin_amdgcn_sched_barrier(0)
; template <class Epi, class Sched, bool ALIGN_EPI = false, bool SP2 = false>
; __device__ __forceinline__ void gemm_phase(PG8_LAS unsigned char* lds, const Gemm g, const Sched& S, const Epi& E) {
;     ...
;             PG8_LDB(B0, 0, 0); PG8_LDB(B1, 0, 1); PG8_SCHED; PG8_LDA(At, 0, 0); PG8_STAGE(PG8_SA(1, 1), a1 + hstepA, voffA);
;             PG8_WAIT_V(8); PG8_WAIT_L(0); PG8_BAR; PG8_MMA(0, 0, At, B0); PG8_MMA(0, 1, At, B1); PG8_BAR; PG8_SCHED;
;             PG8_LDA(At, 0, 1); PG8_STAGE(PG8_SB(0, 0), b2, voffB); PG8_STAGE(PG8_SB(0, 1), b2 + hstepB, voffB); PG8_STAGE(PG8_SA(0, 0), a2, voffA);
;             PG8_WAIT_V(8); PG8_WAIT_L(0); PG8_BAR; PG8_MMA(1, 0, At, B0); PG8_MMA(1, 1, At, B1); PG8_BAR; PG8_SCHED;
.Lsp_LBB0_990:
.LBB0_990:
	ds_read_b128 v[146:149], v154
	ds_read_b128 v[158:161], v154 offset:1024
	ds_read_b128 v[162:165], v154 offset:2048
	ds_read_b128 v[166:169], v154 offset:3072
	ds_read_b128 v[170:173], v155
	ds_read_b128 v[174:177], v155 offset:1024
	ds_read_b128 v[178:181], v155 offset:2048
	ds_read_b128 v[182:185], v155 offset:3072
	s_add_u32 s34, s40, 0xfff00080
	s_addc_u32 s35, s41, -1
	s_cmp_eq_u32 s74, 60
	s_cselect_b32 s35, s23, s35
	s_cselect_b32 s34, s27, s34
	s_cselect_b32 s43, s21, s73
	s_cselect_b32 s42, s39, s72
	s_add_i32 m0, s45, 0xc000
	ds_read_b128 v[186:189], v156
	ds_read_b128 v[190:193], v156 offset:1024
	ds_read_b128 v[194:197], v156 offset:2048
	ds_read_b128 v[198:201], v156 offset:3072
	ds_read_b128 v[202:205], v156 offset:4096
	ds_read_b128 v[206:209], v156 offset:5120
	ds_read_b128 v[210:213], v156 offset:6144
	ds_read_b128 v[214:217], v156 offset:7168
	global_load_lds_dwordx4 v138, s[40:41]
	s_add_i32 m0, s45, 0xe000
	s_nop 0
	global_load_lds_dwordx4 v140, s[40:41]
	s_waitcnt vmcnt(8)
	s_waitcnt lgkmcnt(0)
	s_barrier
	s_waitcnt lgkmcnt(0)
	.p2align 3
	v_mfma_f32_16x16x32_bf16 v[126:129], v[146:149], v[186:189], v[126:129]
	v_mfma_f32_16x16x32_bf16 v[122:125], v[162:165], v[186:189], v[122:125]
	v_mfma_f32_16x16x32_bf16 v[118:121], v[146:149], v[194:197], v[118:121]
	v_mfma_f32_16x16x32_bf16 v[114:117], v[162:165], v[194:197], v[114:117]
	v_mfma_f32_16x16x32_bf16 v[110:113], v[146:149], v[202:205], v[110:113]
	v_mfma_f32_16x16x32_bf16 v[106:109], v[162:165], v[202:205], v[106:109]
	v_mfma_f32_16x16x32_bf16 v[102:105], v[146:149], v[210:213], v[102:105]
	v_mfma_f32_16x16x32_bf16 v[98:101], v[162:165], v[210:213], v[98:101]
	v_mfma_f32_16x16x32_bf16 v[126:129], v[158:161], v[190:193], v[126:129]
	v_mfma_f32_16x16x32_bf16 v[122:125], v[166:169], v[190:193], v[122:125]
	v_mfma_f32_16x16x32_bf16 v[118:121], v[158:161], v[198:201], v[118:121]
	v_mfma_f32_16x16x32_bf16 v[114:117], v[166:169], v[198:201], v[114:117]
	v_mfma_f32_16x16x32_bf16 v[110:113], v[158:161], v[206:209], v[110:113]
	v_mfma_f32_16x16x32_bf16 v[106:109], v[166:169], v[206:209], v[106:109]
	v_mfma_f32_16x16x32_bf16 v[102:105], v[158:161], v[214:217], v[102:105]
	v_mfma_f32_16x16x32_bf16 v[98:101], v[166:169], v[214:217], v[98:101]
	v_mfma_f32_16x16x32_bf16 v[62:65], v[170:173], v[186:189], v[62:65]
	v_mfma_f32_16x16x32_bf16 v[58:61], v[178:181], v[186:189], v[58:61]
	v_mfma_f32_16x16x32_bf16 v[54:57], v[170:173], v[194:197], v[54:57]
	v_mfma_f32_16x16x32_bf16 v[50:53], v[178:181], v[194:197], v[50:53]
	v_mfma_f32_16x16x32_bf16 v[46:49], v[170:173], v[202:205], v[46:49]
	v_mfma_f32_16x16x32_bf16 v[42:45], v[178:181], v[202:205], v[42:45]
	v_mfma_f32_16x16x32_bf16 v[38:41], v[170:173], v[210:213], v[38:41]
	v_mfma_f32_16x16x32_bf16 v[34:37], v[178:181], v[210:213], v[34:37]
	v_mfma_f32_16x16x32_bf16 v[62:65], v[174:177], v[190:193], v[62:65]
	v_mfma_f32_16x16x32_bf16 v[58:61], v[182:185], v[190:193], v[58:61]
	v_mfma_f32_16x16x32_bf16 v[54:57], v[174:177], v[198:201], v[54:57]
	v_mfma_f32_16x16x32_bf16 v[50:53], v[182:185], v[198:201], v[50:53]
	v_mfma_f32_16x16x32_bf16 v[46:49], v[174:177], v[206:209], v[46:49]
	v_mfma_f32_16x16x32_bf16 v[42:45], v[182:185], v[206:209], v[42:45]
	v_mfma_f32_16x16x32_bf16 v[38:41], v[174:177], v[214:217], v[38:41]
	v_mfma_f32_16x16x32_bf16 v[34:37], v[182:185], v[214:217], v[34:37]
	s_barrier
	s_add_i32 s75, s64, s17
	s_add_u32 s98, s42, 0x80
	s_addc_u32 s99, s43, 0
	s_add_u32 s100, s34, 0x80
	s_addc_u32 s101, s35, 0
	s_mov_b32 m0, s75
	ds_read_b128 v[186:189], v156 offset:16384
	ds_read_b128 v[190:193], v156 offset:17408
	ds_read_b128 v[194:197], v156 offset:18432
	ds_read_b128 v[198:201], v156 offset:19456
	ds_read_b128 v[202:205], v156 offset:20480
	ds_read_b128 v[206:209], v156 offset:21504
	ds_read_b128 v[210:213], v156 offset:22528
	ds_read_b128 v[214:217], v156 offset:23552
	global_load_lds_dwordx4 v134, s[42:43]
	s_add_i32 m0, s75, 0x2000
	s_add_u32 s76, s42, 0x100000
	s_addc_u32 s77, s43, 0
	s_add_i32 s75, s65, s17
	global_load_lds_dwordx4 v130, s[42:43]
	s_mov_b32 m0, s75
	s_nop 0
	global_load_lds_dwordx4 v134, s[76:77]
	s_add_i32 m0, s75, 0x2000
	s_nop 0
	global_load_lds_dwordx4 v130, s[76:77]
	s_mov_b32 m0, s45
	s_nop 0
	global_load_lds_dwordx4 v136, s[34:35]
	s_mov_b32 m0, s46
	s_nop 0
	global_load_lds_dwordx4 v132, s[34:35]
	s_waitcnt vmcnt(8)
	s_waitcnt lgkmcnt(0)
	s_barrier
	s_waitcnt lgkmcnt(0)
	.p2align 3
	v_mfma_f32_16x16x32_bf16 v[94:97], v[146:149], v[186:189], v[94:97]
	v_mfma_f32_16x16x32_bf16 v[90:93], v[162:165], v[186:189], v[90:93]
	v_mfma_f32_16x16x32_bf16 v[86:89], v[146:149], v[194:197], v[86:89]
	v_mfma_f32_16x16x32_bf16 v[82:85], v[162:165], v[194:197], v[82:85]
	v_mfma_f32_16x16x32_bf16 v[78:81], v[146:149], v[202:205], v[78:81]
	v_mfma_f32_16x16x32_bf16 v[74:77], v[162:165], v[202:205], v[74:77]
	v_mfma_f32_16x16x32_bf16 v[70:73], v[146:149], v[210:213], v[70:73]
	v_mfma_f32_16x16x32_bf16 v[66:69], v[162:165], v[210:213], v[66:69]
	v_mfma_f32_16x16x32_bf16 v[94:97], v[158:161], v[190:193], v[94:97]
	v_mfma_f32_16x16x32_bf16 v[90:93], v[166:169], v[190:193], v[90:93]
	v_mfma_f32_16x16x32_bf16 v[86:89], v[158:161], v[198:201], v[86:89]
	v_mfma_f32_16x16x32_bf16 v[82:85], v[166:169], v[198:201], v[82:85]
	v_mfma_f32_16x16x32_bf16 v[78:81], v[158:161], v[206:209], v[78:81]
	v_mfma_f32_16x16x32_bf16 v[74:77], v[166:169], v[206:209], v[74:77]
	v_mfma_f32_16x16x32_bf16 v[70:73], v[158:161], v[214:217], v[70:73]
	v_mfma_f32_16x16x32_bf16 v[66:69], v[166:169], v[214:217], v[66:69]
	v_mfma_f32_16x16x32_bf16 v[30:33], v[170:173], v[186:189], v[30:33]
	v_mfma_f32_16x16x32_bf16 v[26:29], v[178:181], v[186:189], v[26:29]
	v_mfma_f32_16x16x32_bf16 v[22:25], v[170:173], v[194:197], v[22:25]
	v_mfma_f32_16x16x32_bf16 v[18:21], v[178:181], v[194:197], v[18:21]
	v_mfma_f32_16x16x32_bf16 v[14:17], v[170:173], v[202:205], v[14:17]
	v_mfma_f32_16x16x32_bf16 v[10:13], v[178:181], v[202:205], v[10:13]
	v_mfma_f32_16x16x32_bf16 v[6:9], v[170:173], v[210:213], v[6:9]
	v_mfma_f32_16x16x32_bf16 v[2:5], v[178:181], v[210:213], v[2:5]
	v_mfma_f32_16x16x32_bf16 v[30:33], v[174:177], v[190:193], v[30:33]
	v_mfma_f32_16x16x32_bf16 v[26:29], v[182:185], v[190:193], v[26:29]
	v_mfma_f32_16x16x32_bf16 v[22:25], v[174:177], v[198:201], v[22:25]
	v_mfma_f32_16x16x32_bf16 v[18:21], v[182:185], v[198:201], v[18:21]
	v_mfma_f32_16x16x32_bf16 v[14:17], v[174:177], v[206:209], v[14:17]
	v_mfma_f32_16x16x32_bf16 v[10:13], v[182:185], v[206:209], v[10:13]
	v_mfma_f32_16x16x32_bf16 v[6:9], v[174:177], v[214:217], v[6:9]
	v_mfma_f32_16x16x32_bf16 v[2:5], v[182:185], v[214:217], v[2:5]
	s_barrier
; #define PG8_STAGE(bufoff, gbase, voff) do { _Pragma("unroll") for (int _i = 0; _i < 2; ++_i) \
;         __builtin_amdgcn_global_load_lds((const unsigned*)((const char*)(gbase) + (voff)[_i]), (PG8_LAS unsigned*)(lds + (bufoff) + ldsw + _i * 8192), 16, 0, 0); } while (0)
; #define PG8_LDA(dst, b, h) do { _Pragma("unroll") for (int m = 0; m < 4; ++m) _Pragma("unroll") for (int k = 0; k < 2; ++k) dst[m][k] = *(const PG8_LAS bf16x8*)(lds + PG8_SA(b, h) + aoff + m * 2048 + k * 1024); } while (0)
; #define PG8_LDB(dst, b, h) do { _Pragma("unroll") for (int n = 0; n < 2; ++n) _Pragma("unroll") for (int k = 0; k < 2; ++k) dst[n][k] = *(const PG8_LAS bf16x8*)(lds + PG8_SB(b, h) + boff + n * 2048 + k * 1024); } while (0)
; #define PG8_MMA(ai, bj, At, Bt) do { __builtin_amdgcn_s_setprio(1); _Pragma("unroll") for (int m = 0; m < 4; ++m) _Pragma("unroll") for (int n = 0; n < 2; ++n) _Pragma("unroll") for (int k = 0; k < 2; ++k) \
;         acc[ai][bj][m][n] = __builtin_amdgcn_mfma_f32_16x16x32_bf16(Bt[n][k], At[m][k], acc[ai][bj][m][n], 0, 0, 0); __builtin_amdgcn_s_setprio(0); } while (0)
; #define PG8_WAIT_V(n) asm volatile("s_waitcnt vmcnt(" #n ")" ::: "memory")
; #define PG8_WAIT_L(n) asm volatile("s_waitcnt lgkmcnt(" #n ")" ::: "memory")
; #define PG8_BAR __builtin_amdgcn_s_barrier()
; #define PG8_SCHED __builtin_amdgcn_sched_barrier(0)
; template <class Epi, class Sched, bool ALIGN_EPI = false, bool SP2 = false>
; __device__ __forceinline__ void gemm_phase(PG8_LAS unsigned char* lds, const Gemm g, const Sched& S, const Epi& E) {
;     ...
;             PG8_LDB(B0, 1, 0); PG8_LDB(B1, 1, 1); PG8_SCHED; PG8_LDA(At, 1, 0); PG8_STAGE(PG8_SA(0, 1), a2 + hstepA, voffA);
;             PG8_WAIT_V(8); PG8_WAIT_L(0); PG8_BAR; PG8_MMA(0, 0, At, B0); PG8_MMA(0, 1, At, B1); PG8_BAR; PG8_SCHED;
;             PG8_LDA(At, 1, 1); PG8_STAGE(PG8_SB(1, 0), b3, voffB); PG8_STAGE(PG8_SB(1, 1), b3 + hstepB, voffB); PG8_STAGE(PG8_SA(1, 0), a3, voffA);
;             PG8_WAIT_V(8); PG8_WAIT_L(0); PG8_BAR; PG8_MMA(1, 0, At, B0); PG8_MMA(1, 1, At, B1); PG8_BAR; PG8_SCHED;
	s_add_i32 s75, 0, 0x18000
	v_add_u32_e32 v157, s75, v152
	s_add_i32 s76, 0, 0x1c000
	ds_read_b128 v[146:149], v157
	ds_read_b128 v[158:161], v157 offset:1024
	ds_read_b128 v[162:165], v157 offset:2048
	ds_read_b128 v[166:169], v157 offset:3072
	v_add_u32_e32 v157, s76, v152
	ds_read_b128 v[170:173], v157
	ds_read_b128 v[174:177], v157 offset:1024
	ds_read_b128 v[178:181], v157 offset:2048
	ds_read_b128 v[182:185], v157 offset:3072
	s_add_u32 s34, s34, 0x100000
	s_addc_u32 s35, s35, 0
	s_mov_b32 m0, s47
	ds_read_b128 v[186:189], v156 offset:32768
	ds_read_b128 v[190:193], v156 offset:33792
	ds_read_b128 v[194:197], v156 offset:34816
	ds_read_b128 v[198:201], v156 offset:35840
	ds_read_b128 v[202:205], v156 offset:36864
	ds_read_b128 v[206:209], v156 offset:37888
	ds_read_b128 v[210:213], v156 offset:38912
	ds_read_b128 v[214:217], v156 offset:39936
	global_load_lds_dwordx4 v136, s[34:35]
	s_mov_b32 m0, s48
	s_nop 0
	global_load_lds_dwordx4 v132, s[34:35]
	s_waitcnt vmcnt(8)
	s_waitcnt lgkmcnt(0)
	s_barrier
	s_waitcnt lgkmcnt(0)
	.p2align 3
	v_mfma_f32_16x16x32_bf16 v[126:129], v[146:149], v[186:189], v[126:129]
	v_mfma_f32_16x16x32_bf16 v[122:125], v[162:165], v[186:189], v[122:125]
	v_mfma_f32_16x16x32_bf16 v[118:121], v[146:149], v[194:197], v[118:121]
	v_mfma_f32_16x16x32_bf16 v[114:117], v[162:165], v[194:197], v[114:117]
	v_mfma_f32_16x16x32_bf16 v[110:113], v[146:149], v[202:205], v[110:113]
	v_mfma_f32_16x16x32_bf16 v[106:109], v[162:165], v[202:205], v[106:109]
	v_mfma_f32_16x16x32_bf16 v[102:105], v[146:149], v[210:213], v[102:105]
	v_mfma_f32_16x16x32_bf16 v[98:101], v[162:165], v[210:213], v[98:101]
	v_mfma_f32_16x16x32_bf16 v[126:129], v[158:161], v[190:193], v[126:129]
	v_mfma_f32_16x16x32_bf16 v[122:125], v[166:169], v[190:193], v[122:125]
	v_mfma_f32_16x16x32_bf16 v[118:121], v[158:161], v[198:201], v[118:121]
	v_mfma_f32_16x16x32_bf16 v[114:117], v[166:169], v[198:201], v[114:117]
	v_mfma_f32_16x16x32_bf16 v[110:113], v[158:161], v[206:209], v[110:113]
	v_mfma_f32_16x16x32_bf16 v[106:109], v[166:169], v[206:209], v[106:109]
	v_mfma_f32_16x16x32_bf16 v[102:105], v[158:161], v[214:217], v[102:105]
	v_mfma_f32_16x16x32_bf16 v[98:101], v[166:169], v[214:217], v[98:101]
	v_mfma_f32_16x16x32_bf16 v[62:65], v[170:173], v[186:189], v[62:65]
	v_mfma_f32_16x16x32_bf16 v[58:61], v[178:181], v[186:189], v[58:61]
	v_mfma_f32_16x16x32_bf16 v[54:57], v[170:173], v[194:197], v[54:57]
	v_mfma_f32_16x16x32_bf16 v[50:53], v[178:181], v[194:197], v[50:53]
	v_mfma_f32_16x16x32_bf16 v[46:49], v[170:173], v[202:205], v[46:49]
	v_mfma_f32_16x16x32_bf16 v[42:45], v[178:181], v[202:205], v[42:45]
	v_mfma_f32_16x16x32_bf16 v[38:41], v[170:173], v[210:213], v[38:41]
	v_mfma_f32_16x16x32_bf16 v[34:37], v[178:181], v[210:213], v[34:37]
	v_mfma_f32_16x16x32_bf16 v[62:65], v[174:177], v[190:193], v[62:65]
	v_mfma_f32_16x16x32_bf16 v[58:61], v[182:185], v[190:193], v[58:61]
	v_mfma_f32_16x16x32_bf16 v[54:57], v[174:177], v[198:201], v[54:57]
	v_mfma_f32_16x16x32_bf16 v[50:53], v[182:185], v[198:201], v[50:53]
	v_mfma_f32_16x16x32_bf16 v[46:49], v[174:177], v[206:209], v[46:49]
	v_mfma_f32_16x16x32_bf16 v[42:45], v[182:185], v[206:209], v[42:45]
	v_mfma_f32_16x16x32_bf16 v[38:41], v[174:177], v[214:217], v[38:41]
	v_mfma_f32_16x16x32_bf16 v[34:37], v[182:185], v[214:217], v[34:37]
	s_barrier
	s_add_i32 s34, s75, s17
	s_mov_b32 m0, s34
	ds_read_b128 v[186:189], v156 offset:49152
	ds_read_b128 v[190:193], v156 offset:50176
	ds_read_b128 v[194:197], v156 offset:51200
	ds_read_b128 v[198:201], v156 offset:52224
	ds_read_b128 v[202:205], v156 offset:53248
	ds_read_b128 v[206:209], v156 offset:54272
	ds_read_b128 v[210:213], v156 offset:55296
	ds_read_b128 v[214:217], v156 offset:56320
	global_load_lds_dwordx4 v134, s[98:99]
	s_add_i32 m0, s34, 0x2000
	s_add_u32 s34, s42, 0x100080
	s_addc_u32 s35, s43, 0
	s_add_i32 s42, s76, s17
	global_load_lds_dwordx4 v130, s[98:99]
	s_mov_b32 m0, s42
	s_nop 0
	global_load_lds_dwordx4 v134, s[34:35]
	s_add_i32 m0, s42, 0x2000
	s_nop 0
	global_load_lds_dwordx4 v130, s[34:35]
	s_mov_b32 m0, s52
	s_nop 0
	global_load_lds_dwordx4 v136, s[100:101]
	s_mov_b32 m0, s53
	s_nop 0
	global_load_lds_dwordx4 v132, s[100:101]
	s_waitcnt vmcnt(8)
	s_waitcnt lgkmcnt(0)
	s_barrier
	s_waitcnt lgkmcnt(0)
	.p2align 3
	v_mfma_f32_16x16x32_bf16 v[94:97], v[146:149], v[186:189], v[94:97]
	v_mfma_f32_16x16x32_bf16 v[90:93], v[162:165], v[186:189], v[90:93]
	v_mfma_f32_16x16x32_bf16 v[86:89], v[146:149], v[194:197], v[86:89]
	v_mfma_f32_16x16x32_bf16 v[82:85], v[162:165], v[194:197], v[82:85]
	v_mfma_f32_16x16x32_bf16 v[78:81], v[146:149], v[202:205], v[78:81]
	v_mfma_f32_16x16x32_bf16 v[74:77], v[162:165], v[202:205], v[74:77]
	v_mfma_f32_16x16x32_bf16 v[70:73], v[146:149], v[210:213], v[70:73]
	v_mfma_f32_16x16x32_bf16 v[66:69], v[162:165], v[210:213], v[66:69]
	v_mfma_f32_16x16x32_bf16 v[94:97], v[158:161], v[190:193], v[94:97]
	v_mfma_f32_16x16x32_bf16 v[90:93], v[166:169], v[190:193], v[90:93]
	v_mfma_f32_16x16x32_bf16 v[86:89], v[158:161], v[198:201], v[86:89]
	v_mfma_f32_16x16x32_bf16 v[82:85], v[166:169], v[198:201], v[82:85]
	v_mfma_f32_16x16x32_bf16 v[78:81], v[158:161], v[206:209], v[78:81]
	v_mfma_f32_16x16x32_bf16 v[74:77], v[166:169], v[206:209], v[74:77]
	v_mfma_f32_16x16x32_bf16 v[70:73], v[158:161], v[214:217], v[70:73]
	v_mfma_f32_16x16x32_bf16 v[66:69], v[166:169], v[214:217], v[66:69]
	v_mfma_f32_16x16x32_bf16 v[30:33], v[170:173], v[186:189], v[30:33]
	v_mfma_f32_16x16x32_bf16 v[26:29], v[178:181], v[186:189], v[26:29]
	v_mfma_f32_16x16x32_bf16 v[22:25], v[170:173], v[194:197], v[22:25]
	v_mfma_f32_16x16x32_bf16 v[18:21], v[178:181], v[194:197], v[18:21]
	v_mfma_f32_16x16x32_bf16 v[14:17], v[170:173], v[202:205], v[14:17]
	v_mfma_f32_16x16x32_bf16 v[10:13], v[178:181], v[202:205], v[10:13]
	v_mfma_f32_16x16x32_bf16 v[6:9], v[170:173], v[210:213], v[6:9]
	v_mfma_f32_16x16x32_bf16 v[2:5], v[178:181], v[210:213], v[2:5]
	v_mfma_f32_16x16x32_bf16 v[30:33], v[174:177], v[190:193], v[30:33]
	v_mfma_f32_16x16x32_bf16 v[26:29], v[182:185], v[190:193], v[26:29]
	v_mfma_f32_16x16x32_bf16 v[22:25], v[174:177], v[198:201], v[22:25]
	v_mfma_f32_16x16x32_bf16 v[18:21], v[182:185], v[198:201], v[18:21]
	v_mfma_f32_16x16x32_bf16 v[14:17], v[174:177], v[206:209], v[14:17]
	v_mfma_f32_16x16x32_bf16 v[10:13], v[182:185], v[206:209], v[10:13]
	v_mfma_f32_16x16x32_bf16 v[6:9], v[174:177], v[214:217], v[6:9]
	v_mfma_f32_16x16x32_bf16 v[2:5], v[182:185], v[214:217], v[2:5]
	s_barrier
	s_add_i32 s74, s74, 2
	s_add_u32 s40, s40, 0x100
	s_addc_u32 s41, s41, 0
	s_add_u32 s72, s72, 0x100
	s_addc_u32 s73, s73, 0
	s_cmp_gt_u32 s74, 61
	s_cbranch_scc0 .LBB0_990
	s_setprio 0
	s_and_b64 vcc, exec, s[12:13]
	s_cbranch_vccz .LBB0_993
	s_barrier

; #define PG8_STAGE(bufoff, gbase, voff) do { _Pragma("unroll") for (int _i = 0; _i < 2; ++_i) \
;         __builtin_amdgcn_global_load_lds((const unsigned*)((const char*)(gbase) + (voff)[_i]), (PG8_LAS unsigned*)(lds + (bufoff) + ldsw + _i * 8192), 16, 0, 0); } while (0)
; #define PG8_LDA(dst, b, h) do { _Pragma("unroll") for (int m = 0; m < 4; ++m) _Pragma("unroll") for (int k = 0; k < 2; ++k) dst[m][k] = *(const PG8_LAS bf16x8*)(lds + PG8_SA(b, h) + aoff + m * 2048 + k * 1024); } while (0)
; #define PG8_LDB(dst, b, h) do { _Pragma("unroll") for (int n = 0; n < 2; ++n) _Pragma("unroll") for (int k = 0; k < 2; ++k) dst[n][k] = *(const PG8_LAS bf16x8*)(lds + PG8_SB(b, h) + boff + n * 2048 + k * 1024); } while (0)
; #define PG8_MMA(ai, bj, At, Bt) do { __builtin_amdgcn_s_setprio(1); _Pragma("unroll") for (int m = 0; m < 4; ++m) _Pragma("unroll") for (int n = 0; n < 2; ++n) _Pragma("unroll") for (int k = 0; k < 2; ++k) \
;         acc[ai][bj][m][n] = __builtin_amdgcn_mfma_f32_16x16x32_bf16(Bt[n][k], At[m][k], acc[ai][bj][m][n], 0, 0, 0); __builtin_amdgcn_s_setprio(0); } while (0)
; #define PG8_WAIT_V(n) asm volatile("s_waitcnt vmcnt(" #n ")" ::: "memory")
; #define PG8_WAIT_L(n) asm volatile("s_waitcnt lgkmcnt(" #n ")" ::: "memory")
; #define PG8_BAR __builtin_amdgcn_s_barrier()
; #define PG8_SCHED __builtin_amdgcn_sched_barrier(0)
; template <class Epi, class Sched, bool ALIGN_EPI = false, bool SP2 = false>
; __device__ __forceinline__ void gemm_phase(PG8_LAS unsigned char* lds, const Gemm g, const Sched& S, const Epi& E) {
;     ...
;             PG8_LDB(B0, 0, 0); PG8_LDB(B1, 0, 1); PG8_SCHED; PG8_LDA(At, 0, 0); PG8_STAGE(PG8_SA(1, 1), a1 + hstepA, voffA);
;             PG8_WAIT_V(8); PG8_WAIT_L(0); PG8_BAR; PG8_MMA(0, 0, At, B0); PG8_MMA(0, 1, At, B1); PG8_BAR; PG8_SCHED;
;             PG8_LDA(At, 0, 1); PG8_STAGE(PG8_SB(0, 0), b2, voffB); PG8_STAGE(PG8_SB(0, 1), b2 + hstepB, voffB); PG8_STAGE(PG8_SA(0, 0), a2, voffA);
;             PG8_WAIT_V(8); PG8_WAIT_L(0); PG8_BAR; PG8_MMA(1, 0, At, B0); PG8_MMA(1, 1, At, B1); PG8_BAR; PG8_SCHED;
.Lsp_LBB0_1127:
.LBB0_1127:
	ds_read_b128 v[130:133], v203
	ds_read_b128 v[134:137], v203 offset:1024
	ds_read_b128 v[138:141], v203 offset:2048
	ds_read_b128 v[142:145], v203 offset:3072
	ds_read_b128 v[146:149], v205
	ds_read_b128 v[150:153], v205 offset:1024
	ds_read_b128 v[154:157], v205 offset:2048
	ds_read_b128 v[158:161], v205 offset:3072
	s_add_u32 s34, s40, 0xfff00080
	s_addc_u32 s35, s41, -1
	s_cmp_eq_u32 s53, 60
	s_cselect_b32 s35, s25, s35
	s_cselect_b32 s34, s26, s34
	s_cselect_b32 s43, s23, s52
	s_cselect_b32 s42, s27, s45
	s_add_i32 m0, s47, 0xc000
	ds_read_b128 v[162:165], v207
	ds_read_b128 v[166:169], v207 offset:1024
	ds_read_b128 v[170:173], v207 offset:2048
	ds_read_b128 v[174:177], v207 offset:3072
	ds_read_b128 v[196:199], v207 offset:4096
	ds_read_b128 v[208:211], v207 offset:5120
	ds_read_b128 v[212:215], v207 offset:6144
	ds_read_b128 v[216:219], v207 offset:7168
	global_load_lds_dwordx4 v188, s[40:41]
	s_add_i32 m0, s47, 0xe000
	s_nop 0
	global_load_lds_dwordx4 v190, s[40:41]
	s_waitcnt vmcnt(8)
	s_waitcnt lgkmcnt(0)
	s_barrier
	s_waitcnt lgkmcnt(0)
	.p2align 3
	v_mfma_f32_16x16x32_bf16 v[122:125], v[130:133], v[162:165], v[122:125]
	v_mfma_f32_16x16x32_bf16 v[118:121], v[138:141], v[162:165], v[118:121]
	v_mfma_f32_16x16x32_bf16 v[106:109], v[130:133], v[170:173], v[106:109]
	v_mfma_f32_16x16x32_bf16 v[102:105], v[138:141], v[170:173], v[102:105]
	v_mfma_f32_16x16x32_bf16 v[90:93], v[130:133], v[196:199], v[90:93]
	v_mfma_f32_16x16x32_bf16 v[86:89], v[138:141], v[196:199], v[86:89]
	v_mfma_f32_16x16x32_bf16 v[74:77], v[130:133], v[212:215], v[74:77]
	v_mfma_f32_16x16x32_bf16 v[70:73], v[138:141], v[212:215], v[70:73]
	v_mfma_f32_16x16x32_bf16 v[122:125], v[134:137], v[166:169], v[122:125]
	v_mfma_f32_16x16x32_bf16 v[118:121], v[142:145], v[166:169], v[118:121]
	v_mfma_f32_16x16x32_bf16 v[106:109], v[134:137], v[174:177], v[106:109]
	v_mfma_f32_16x16x32_bf16 v[102:105], v[142:145], v[174:177], v[102:105]
	v_mfma_f32_16x16x32_bf16 v[90:93], v[134:137], v[208:211], v[90:93]
	v_mfma_f32_16x16x32_bf16 v[86:89], v[142:145], v[208:211], v[86:89]
	v_mfma_f32_16x16x32_bf16 v[74:77], v[134:137], v[216:219], v[74:77]
	v_mfma_f32_16x16x32_bf16 v[70:73], v[142:145], v[216:219], v[70:73]
	v_mfma_f32_16x16x32_bf16 v[126:129], v[146:149], v[162:165], v[126:129]
	v_mfma_f32_16x16x32_bf16 v[114:117], v[154:157], v[162:165], v[114:117]
	v_mfma_f32_16x16x32_bf16 v[110:113], v[146:149], v[170:173], v[110:113]
	v_mfma_f32_16x16x32_bf16 v[98:101], v[154:157], v[170:173], v[98:101]
	v_mfma_f32_16x16x32_bf16 v[94:97], v[146:149], v[196:199], v[94:97]
	v_mfma_f32_16x16x32_bf16 v[82:85], v[154:157], v[196:199], v[82:85]
	v_mfma_f32_16x16x32_bf16 v[78:81], v[146:149], v[212:215], v[78:81]
	v_mfma_f32_16x16x32_bf16 v[66:69], v[154:157], v[212:215], v[66:69]
	v_mfma_f32_16x16x32_bf16 v[126:129], v[150:153], v[166:169], v[126:129]
	v_mfma_f32_16x16x32_bf16 v[114:117], v[158:161], v[166:169], v[114:117]
	v_mfma_f32_16x16x32_bf16 v[110:113], v[150:153], v[174:177], v[110:113]
	v_mfma_f32_16x16x32_bf16 v[98:101], v[158:161], v[174:177], v[98:101]
	v_mfma_f32_16x16x32_bf16 v[94:97], v[150:153], v[208:211], v[94:97]
	v_mfma_f32_16x16x32_bf16 v[82:85], v[158:161], v[208:211], v[82:85]
	v_mfma_f32_16x16x32_bf16 v[78:81], v[150:153], v[216:219], v[78:81]
	v_mfma_f32_16x16x32_bf16 v[66:69], v[158:161], v[216:219], v[66:69]
	s_barrier
	s_add_i32 s73, s68, s17
	s_add_u32 s98, s42, 0x80
	s_addc_u32 s99, s43, 0
	s_add_u32 s100, s34, 0x80
	s_addc_u32 s101, s35, 0
	s_mov_b32 m0, s73
	ds_read_b128 v[162:165], v207 offset:16384
	ds_read_b128 v[166:169], v207 offset:17408
	ds_read_b128 v[170:173], v207 offset:18432
	ds_read_b128 v[174:177], v207 offset:19456
	ds_read_b128 v[196:199], v207 offset:20480
	ds_read_b128 v[208:211], v207 offset:21504
	ds_read_b128 v[212:215], v207 offset:22528
	ds_read_b128 v[216:219], v207 offset:23552
	global_load_lds_dwordx4 v182, s[42:43]
	s_add_i32 m0, s73, 0x2000
	s_add_u32 s74, s42, 0x100000
	s_addc_u32 s75, s43, 0
	s_add_i32 s73, s69, s17
	global_load_lds_dwordx4 v178, s[42:43]
	s_mov_b32 m0, s73
	s_nop 0
	global_load_lds_dwordx4 v182, s[74:75]
	s_add_i32 m0, s73, 0x2000
	s_nop 0
	global_load_lds_dwordx4 v178, s[74:75]
	s_mov_b32 m0, s47
	s_nop 0
	global_load_lds_dwordx4 v184, s[34:35]
	s_mov_b32 m0, s48
	s_nop 0
	global_load_lds_dwordx4 v180, s[34:35]
	s_waitcnt vmcnt(8)
	s_waitcnt lgkmcnt(0)
	s_barrier
	s_waitcnt lgkmcnt(0)
	.p2align 3
	v_mfma_f32_16x16x32_bf16 v[58:61], v[130:133], v[162:165], v[58:61]
	v_mfma_f32_16x16x32_bf16 v[54:57], v[138:141], v[162:165], v[54:57]
	v_mfma_f32_16x16x32_bf16 v[42:45], v[130:133], v[170:173], v[42:45]
	v_mfma_f32_16x16x32_bf16 v[38:41], v[138:141], v[170:173], v[38:41]
	v_mfma_f32_16x16x32_bf16 v[26:29], v[130:133], v[196:199], v[26:29]
	v_mfma_f32_16x16x32_bf16 v[22:25], v[138:141], v[196:199], v[22:25]
	v_mfma_f32_16x16x32_bf16 v[10:13], v[130:133], v[212:215], v[10:13]
	v_mfma_f32_16x16x32_bf16 v[6:9], v[138:141], v[212:215], v[6:9]
	v_mfma_f32_16x16x32_bf16 v[58:61], v[134:137], v[166:169], v[58:61]
	v_mfma_f32_16x16x32_bf16 v[54:57], v[142:145], v[166:169], v[54:57]
	v_mfma_f32_16x16x32_bf16 v[42:45], v[134:137], v[174:177], v[42:45]
	v_mfma_f32_16x16x32_bf16 v[38:41], v[142:145], v[174:177], v[38:41]
	v_mfma_f32_16x16x32_bf16 v[26:29], v[134:137], v[208:211], v[26:29]
	v_mfma_f32_16x16x32_bf16 v[22:25], v[142:145], v[208:211], v[22:25]
	v_mfma_f32_16x16x32_bf16 v[10:13], v[134:137], v[216:219], v[10:13]
	v_mfma_f32_16x16x32_bf16 v[6:9], v[142:145], v[216:219], v[6:9]
	v_mfma_f32_16x16x32_bf16 v[62:65], v[146:149], v[162:165], v[62:65]
	v_mfma_f32_16x16x32_bf16 v[50:53], v[154:157], v[162:165], v[50:53]
	v_mfma_f32_16x16x32_bf16 v[46:49], v[146:149], v[170:173], v[46:49]
	v_mfma_f32_16x16x32_bf16 v[34:37], v[154:157], v[170:173], v[34:37]
	v_mfma_f32_16x16x32_bf16 v[30:33], v[146:149], v[196:199], v[30:33]
	v_mfma_f32_16x16x32_bf16 v[18:21], v[154:157], v[196:199], v[18:21]
	v_mfma_f32_16x16x32_bf16 v[14:17], v[146:149], v[212:215], v[14:17]
	v_mfma_f32_16x16x32_bf16 v[2:5], v[154:157], v[212:215], v[2:5]
	v_mfma_f32_16x16x32_bf16 v[62:65], v[150:153], v[166:169], v[62:65]
	v_mfma_f32_16x16x32_bf16 v[50:53], v[158:161], v[166:169], v[50:53]
	v_mfma_f32_16x16x32_bf16 v[46:49], v[150:153], v[174:177], v[46:49]
	v_mfma_f32_16x16x32_bf16 v[34:37], v[158:161], v[174:177], v[34:37]
	v_mfma_f32_16x16x32_bf16 v[30:33], v[150:153], v[208:211], v[30:33]
	v_mfma_f32_16x16x32_bf16 v[18:21], v[158:161], v[208:211], v[18:21]
	v_mfma_f32_16x16x32_bf16 v[14:17], v[150:153], v[216:219], v[14:17]
	v_mfma_f32_16x16x32_bf16 v[2:5], v[158:161], v[216:219], v[2:5]
	s_barrier
; #define PG8_STAGE(bufoff, gbase, voff) do { _Pragma("unroll") for (int _i = 0; _i < 2; ++_i) \
;         __builtin_amdgcn_global_load_lds((const unsigned*)((const char*)(gbase) + (voff)[_i]), (PG8_LAS unsigned*)(lds + (bufoff) + ldsw + _i * 8192), 16, 0, 0); } while (0)
; #define PG8_LDA(dst, b, h) do { _Pragma("unroll") for (int m = 0; m < 4; ++m) _Pragma("unroll") for (int k = 0; k < 2; ++k) dst[m][k] = *(const PG8_LAS bf16x8*)(lds + PG8_SA(b, h) + aoff + m * 2048 + k * 1024); } while (0)
; #define PG8_LDB(dst, b, h) do { _Pragma("unroll") for (int n = 0; n < 2; ++n) _Pragma("unroll") for (int k = 0; k < 2; ++k) dst[n][k] = *(const PG8_LAS bf16x8*)(lds + PG8_SB(b, h) + boff + n * 2048 + k * 1024); } while (0)
; #define PG8_MMA(ai, bj, At, Bt) do { __builtin_amdgcn_s_setprio(1); _Pragma("unroll") for (int m = 0; m < 4; ++m) _Pragma("unroll") for (int n = 0; n < 2; ++n) _Pragma("unroll") for (int k = 0; k < 2; ++k) \
;         acc[ai][bj][m][n] = __builtin_amdgcn_mfma_f32_16x16x32_bf16(Bt[n][k], At[m][k], acc[ai][bj][m][n], 0, 0, 0); __builtin_amdgcn_s_setprio(0); } while (0)
; #define PG8_WAIT_V(n) asm volatile("s_waitcnt vmcnt(" #n ")" ::: "memory")
; #define PG8_WAIT_L(n) asm volatile("s_waitcnt lgkmcnt(" #n ")" ::: "memory")
; #define PG8_BAR __builtin_amdgcn_s_barrier()
; #define PG8_SCHED __builtin_amdgcn_sched_barrier(0)
; template <class Epi, class Sched, bool ALIGN_EPI = false, bool SP2 = false>
; __device__ __forceinline__ void gemm_phase(PG8_LAS unsigned char* lds, const Gemm g, const Sched& S, const Epi& E) {
;     ...
;             PG8_LDB(B0, 1, 0); PG8_LDB(B1, 1, 1); PG8_SCHED; PG8_LDA(At, 1, 0); PG8_STAGE(PG8_SA(0, 1), a2 + hstepA, voffA);
;             PG8_WAIT_V(8); PG8_WAIT_L(0); PG8_BAR; PG8_MMA(0, 0, At, B0); PG8_MMA(0, 1, At, B1); PG8_BAR; PG8_SCHED;
;             PG8_LDA(At, 1, 1); PG8_STAGE(PG8_SB(1, 0), b3, voffB); PG8_STAGE(PG8_SB(1, 1), b3 + hstepB, voffB); PG8_STAGE(PG8_SA(1, 0), a3, voffA);
;             PG8_WAIT_V(8); PG8_WAIT_L(0); PG8_BAR; PG8_MMA(1, 0, At, B0); PG8_MMA(1, 1, At, B1); PG8_BAR; PG8_SCHED;
	s_add_i32 s73, 0, 0x18000
	s_add_i32 s74, 0, 0x1c000
	v_add_u32_e32 v142, s73, v1
	v_add_u32_e32 v158, s74, v1
	ds_read_b128 v[130:133], v142
	ds_read_b128 v[134:137], v142 offset:1024
	ds_read_b128 v[138:141], v142 offset:2048
	ds_read_b128 v[142:145], v142 offset:3072
	ds_read_b128 v[146:149], v158
	ds_read_b128 v[150:153], v158 offset:1024
	ds_read_b128 v[154:157], v158 offset:2048
	ds_read_b128 v[158:161], v158 offset:3072
	s_add_u32 s34, s34, 0x100000
	s_addc_u32 s35, s35, 0
	s_mov_b32 m0, s49
	ds_read_b128 v[162:165], v207 offset:32768
	ds_read_b128 v[166:169], v207 offset:33792
	ds_read_b128 v[170:173], v207 offset:34816
	ds_read_b128 v[174:177], v207 offset:35840
	ds_read_b128 v[196:199], v207 offset:36864
	ds_read_b128 v[208:211], v207 offset:37888
	ds_read_b128 v[212:215], v207 offset:38912
	ds_read_b128 v[216:219], v207 offset:39936
	global_load_lds_dwordx4 v184, s[34:35]
	s_mov_b32 m0, s60
	s_nop 0
	global_load_lds_dwordx4 v180, s[34:35]
	s_waitcnt vmcnt(8)
	s_waitcnt lgkmcnt(0)
	s_barrier
	s_waitcnt lgkmcnt(0)
	.p2align 3
	v_mfma_f32_16x16x32_bf16 v[122:125], v[130:133], v[162:165], v[122:125]
	v_mfma_f32_16x16x32_bf16 v[118:121], v[138:141], v[162:165], v[118:121]
	v_mfma_f32_16x16x32_bf16 v[106:109], v[130:133], v[170:173], v[106:109]
	v_mfma_f32_16x16x32_bf16 v[102:105], v[138:141], v[170:173], v[102:105]
	v_mfma_f32_16x16x32_bf16 v[90:93], v[130:133], v[196:199], v[90:93]
	v_mfma_f32_16x16x32_bf16 v[86:89], v[138:141], v[196:199], v[86:89]
	v_mfma_f32_16x16x32_bf16 v[74:77], v[130:133], v[212:215], v[74:77]
	v_mfma_f32_16x16x32_bf16 v[70:73], v[138:141], v[212:215], v[70:73]
	v_mfma_f32_16x16x32_bf16 v[122:125], v[134:137], v[166:169], v[122:125]
	v_mfma_f32_16x16x32_bf16 v[118:121], v[142:145], v[166:169], v[118:121]
	v_mfma_f32_16x16x32_bf16 v[106:109], v[134:137], v[174:177], v[106:109]
	v_mfma_f32_16x16x32_bf16 v[102:105], v[142:145], v[174:177], v[102:105]
	v_mfma_f32_16x16x32_bf16 v[90:93], v[134:137], v[208:211], v[90:93]
	v_mfma_f32_16x16x32_bf16 v[86:89], v[142:145], v[208:211], v[86:89]
	v_mfma_f32_16x16x32_bf16 v[74:77], v[134:137], v[216:219], v[74:77]
	v_mfma_f32_16x16x32_bf16 v[70:73], v[142:145], v[216:219], v[70:73]
	v_mfma_f32_16x16x32_bf16 v[126:129], v[146:149], v[162:165], v[126:129]
	v_mfma_f32_16x16x32_bf16 v[114:117], v[154:157], v[162:165], v[114:117]
	v_mfma_f32_16x16x32_bf16 v[110:113], v[146:149], v[170:173], v[110:113]
	v_mfma_f32_16x16x32_bf16 v[98:101], v[154:157], v[170:173], v[98:101]
	v_mfma_f32_16x16x32_bf16 v[94:97], v[146:149], v[196:199], v[94:97]
	v_mfma_f32_16x16x32_bf16 v[82:85], v[154:157], v[196:199], v[82:85]
	v_mfma_f32_16x16x32_bf16 v[78:81], v[146:149], v[212:215], v[78:81]
	v_mfma_f32_16x16x32_bf16 v[66:69], v[154:157], v[212:215], v[66:69]
	v_mfma_f32_16x16x32_bf16 v[126:129], v[150:153], v[166:169], v[126:129]
	v_mfma_f32_16x16x32_bf16 v[114:117], v[158:161], v[166:169], v[114:117]
	v_mfma_f32_16x16x32_bf16 v[110:113], v[150:153], v[174:177], v[110:113]
	v_mfma_f32_16x16x32_bf16 v[98:101], v[158:161], v[174:177], v[98:101]
	v_mfma_f32_16x16x32_bf16 v[94:97], v[150:153], v[208:211], v[94:97]
	v_mfma_f32_16x16x32_bf16 v[82:85], v[158:161], v[208:211], v[82:85]
	v_mfma_f32_16x16x32_bf16 v[78:81], v[150:153], v[216:219], v[78:81]
	v_mfma_f32_16x16x32_bf16 v[66:69], v[158:161], v[216:219], v[66:69]
	s_barrier
	s_add_i32 s34, s73, s17
	s_mov_b32 m0, s34
	ds_read_b128 v[162:165], v207 offset:49152
	ds_read_b128 v[166:169], v207 offset:50176
	ds_read_b128 v[170:173], v207 offset:51200
	ds_read_b128 v[174:177], v207 offset:52224
	ds_read_b128 v[196:199], v207 offset:53248
	ds_read_b128 v[208:211], v207 offset:54272
	ds_read_b128 v[212:215], v207 offset:55296
	ds_read_b128 v[216:219], v207 offset:56320
	global_load_lds_dwordx4 v182, s[98:99]
	s_add_i32 m0, s34, 0x2000
	s_add_u32 s34, s42, 0x100080
	s_addc_u32 s35, s43, 0
	s_add_i32 s42, s74, s17
	global_load_lds_dwordx4 v178, s[98:99]
	s_mov_b32 m0, s42
	s_nop 0
	global_load_lds_dwordx4 v182, s[34:35]
	s_add_i32 m0, s42, 0x2000
	s_nop 0
	global_load_lds_dwordx4 v178, s[34:35]
	s_mov_b32 m0, s64
	s_nop 0
	global_load_lds_dwordx4 v184, s[100:101]
	s_mov_b32 m0, s65
	s_nop 0
	global_load_lds_dwordx4 v180, s[100:101]
	s_waitcnt vmcnt(8)
	s_waitcnt lgkmcnt(0)
	s_barrier
	s_waitcnt lgkmcnt(0)
	.p2align 3
	v_mfma_f32_16x16x32_bf16 v[58:61], v[130:133], v[162:165], v[58:61]
	v_mfma_f32_16x16x32_bf16 v[54:57], v[138:141], v[162:165], v[54:57]
	v_mfma_f32_16x16x32_bf16 v[42:45], v[130:133], v[170:173], v[42:45]
	v_mfma_f32_16x16x32_bf16 v[38:41], v[138:141], v[170:173], v[38:41]
	v_mfma_f32_16x16x32_bf16 v[26:29], v[130:133], v[196:199], v[26:29]
	v_mfma_f32_16x16x32_bf16 v[22:25], v[138:141], v[196:199], v[22:25]
	v_mfma_f32_16x16x32_bf16 v[10:13], v[130:133], v[212:215], v[10:13]
	v_mfma_f32_16x16x32_bf16 v[6:9], v[138:141], v[212:215], v[6:9]
	v_mfma_f32_16x16x32_bf16 v[58:61], v[134:137], v[166:169], v[58:61]
	v_mfma_f32_16x16x32_bf16 v[54:57], v[142:145], v[166:169], v[54:57]
	v_mfma_f32_16x16x32_bf16 v[42:45], v[134:137], v[174:177], v[42:45]
	v_mfma_f32_16x16x32_bf16 v[38:41], v[142:145], v[174:177], v[38:41]
	v_mfma_f32_16x16x32_bf16 v[26:29], v[134:137], v[208:211], v[26:29]
	v_mfma_f32_16x16x32_bf16 v[22:25], v[142:145], v[208:211], v[22:25]
	v_mfma_f32_16x16x32_bf16 v[10:13], v[134:137], v[216:219], v[10:13]
	v_mfma_f32_16x16x32_bf16 v[6:9], v[142:145], v[216:219], v[6:9]
	v_mfma_f32_16x16x32_bf16 v[62:65], v[146:149], v[162:165], v[62:65]
	v_mfma_f32_16x16x32_bf16 v[50:53], v[154:157], v[162:165], v[50:53]
	v_mfma_f32_16x16x32_bf16 v[46:49], v[146:149], v[170:173], v[46:49]
	v_mfma_f32_16x16x32_bf16 v[34:37], v[154:157], v[170:173], v[34:37]
	v_mfma_f32_16x16x32_bf16 v[30:33], v[146:149], v[196:199], v[30:33]
	v_mfma_f32_16x16x32_bf16 v[18:21], v[154:157], v[196:199], v[18:21]
	v_mfma_f32_16x16x32_bf16 v[14:17], v[146:149], v[212:215], v[14:17]
	v_mfma_f32_16x16x32_bf16 v[2:5], v[154:157], v[212:215], v[2:5]
	v_mfma_f32_16x16x32_bf16 v[62:65], v[150:153], v[166:169], v[62:65]
	v_mfma_f32_16x16x32_bf16 v[50:53], v[158:161], v[166:169], v[50:53]
	v_mfma_f32_16x16x32_bf16 v[46:49], v[150:153], v[174:177], v[46:49]
	v_mfma_f32_16x16x32_bf16 v[34:37], v[158:161], v[174:177], v[34:37]
	v_mfma_f32_16x16x32_bf16 v[30:33], v[150:153], v[208:211], v[30:33]
	v_mfma_f32_16x16x32_bf16 v[18:21], v[158:161], v[208:211], v[18:21]
	v_mfma_f32_16x16x32_bf16 v[14:17], v[150:153], v[216:219], v[14:17]
	v_mfma_f32_16x16x32_bf16 v[2:5], v[158:161], v[216:219], v[2:5]
	s_barrier
; #define PG8_STAGE(bufoff, gbase, voff) do { _Pragma("unroll") for (int _i = 0; _i < 2; ++_i) \
;         __builtin_amdgcn_global_load_lds((const unsigned*)((const char*)(gbase) + (voff)[_i]), (PG8_LAS unsigned*)(lds + (bufoff) + ldsw + _i * 8192), 16, 0, 0); } while (0)
; #define PG8_LDA(dst, b, h) do { _Pragma("unroll") for (int m = 0; m < 4; ++m) _Pragma("unroll") for (int k = 0; k < 2; ++k) dst[m][k] = *(const PG8_LAS bf16x8*)(lds + PG8_SA(b, h) + aoff + m * 2048 + k * 1024); } while (0)
; #define PG8_LDB(dst, b, h) do { _Pragma("unroll") for (int n = 0; n < 2; ++n) _Pragma("unroll") for (int k = 0; k < 2; ++k) dst[n][k] = *(const PG8_LAS bf16x8*)(lds + PG8_SB(b, h) + boff + n * 2048 + k * 1024); } while (0)
; #define PG8_WAIT_V(n) asm volatile("s_waitcnt vmcnt(" #n ")" ::: "memory")
; #define PG8_WAIT_L(n) asm volatile("s_waitcnt lgkmcnt(" #n ")" ::: "memory")
; template <class Epi, class Sched, bool ALIGN_EPI = false, bool SP2 = false>
; __device__ __forceinline__ void gemm_phase(PG8_LAS unsigned char* lds, const Gemm g, const Sched& S, const Epi& E) {
;     ...
;             PG8_LDB(B0, 0, 0); PG8_LDB(B1, 0, 1); PG8_SCHED; PG8_LDA(At, 0, 0); PG8_STAGE(PG8_SA(1, 1), a1 + hstepA, voffA);
;             PG8_WAIT_V(8); PG8_WAIT_L(0); PG8_BAR; PG8_MMA(0, 0, At, B0); PG8_MMA(0, 1, At, B1); PG8_BAR; PG8_SCHED;
;     __device__ __forceinline__ void operator()(const af4 (&acc)[2][2][4][2], const pg8::Unit& u, int wr_, int wc_, int fr_, int fq_) const {
;     ...
;         float lg[2], lb[2];
; #pragma unroll
;         for (int n = 0; n < 2; ++n) { lg[n] = lng[chl + 4 * n]; lb[n] = lnb[chl + 4 * n]; }
;         v4u raw[2][4];
;         auto load_raw = [&](int ai) {
; #pragma unroll
;             for (int ks = 0; ks < 4; ++ks)
; #pragma unroll
;                 for (int n = 0; n < 2; ++n) raw[n][ks] = *(const GAS v4u*)(VT + (size_t)(chl + 4 * n) * MLAT + u.pm * 256 + ai * 128 + 32 * ks + 8 * fq);
;         };
;         load_raw(0);
; #pragma unroll
;         for (int ai = 0; ai < 2; ++ai) {
;             const int tok0 = u.pm * 256 + ai * 128;
;             bf16x8 av[2][4];
; #pragma unroll
;             for (int ks = 0; ks < 4; ++ks) {
;                 const int j0 = tok0 + 32 * ks + 8 * fq;
;                 f32x4 st[4];
; #pragma unroll
;                 for (int q = 0; q < 4; ++q) st[q] = *(const GAS f32x4*)(stats + (size_t)(j0 + 2 * q) * 2);
	s_add_i32 s53, s53, 2
	s_add_u32 s40, s40, 0x100
	s_addc_u32 s41, s41, 0
	s_add_u32 s45, s45, 0x100
	s_addc_u32 s52, s52, 0
	s_cmp_gt_u32 s53, 59
	s_cbranch_scc0 .LBB0_1127
	ds_read_b128 v[130:133], v203
	ds_read_b128 v[134:137], v203 offset:1024
	ds_read_b128 v[138:141], v203 offset:2048
	ds_read_b128 v[142:145], v203 offset:3072
	ds_read_b128 v[146:149], v205
	ds_read_b128 v[150:153], v205 offset:1024
	ds_read_b128 v[154:157], v205 offset:2048
	ds_read_b128 v[158:161], v205 offset:3072
	s_add_u32 s34, s40, 0xfff00080
	s_addc_u32 s35, s41, -1
	s_cmp_eq_u32 s53, 60
	s_cselect_b32 s35, s25, s35
	s_cselect_b32 s34, s26, s34
	s_cselect_b32 s43, s23, s52
	s_cselect_b32 s42, s27, s45
	s_add_i32 m0, s47, 0xc000
	ds_read_b128 v[162:165], v207
	ds_read_b128 v[166:169], v207 offset:1024
	ds_read_b128 v[170:173], v207 offset:2048
	ds_read_b128 v[174:177], v207 offset:3072
	ds_read_b128 v[196:199], v207 offset:4096
	ds_read_b128 v[208:211], v207 offset:5120
	ds_read_b128 v[212:215], v207 offset:6144
	ds_read_b128 v[216:219], v207 offset:7168
	global_load_lds_dwordx4 v188, s[40:41]
	s_add_i32 m0, s47, 0xe000
	s_nop 0
	global_load_lds_dwordx4 v190, s[40:41]
	v_readlane_b32 s98, v254, 12
	v_readlane_b32 s99, v254, 13
	v_readlane_b32 s100, v254, 14
	v_readlane_b32 s101, v254, 15
	v_readfirstlane_b32 s73, v0
	v_lshlrev_b32_e32 v200, 1, v0
	v_and_b32_e32 v201, 3, v0
	v_and_b32_e32 v200, 24, v200
	s_lshl_b32 s74, s44, 7
	v_or3_b32 v200, v201, v200, s74
	s_lshr_b32 s74, s73, 1
	s_and_b32 s74, s74, 0x60
	v_or_b32_e32 v200, s74, v200
	v_lshlrev_b32_e32 v204, 2, v200
	v_lshrrev_b32_e32 v202, 1, v0
	v_and_b32_e32 v202, 24, v202
	v_lshlrev_b32_e32 v200, 15, v200
	v_lshl_add_u32 v200, v202, 1, v200
	s_lshl_b32 s74, s6, 9
	v_add_u32_e32 v200, s74, v200
	v_add_u32_e32 v201, 0x20000, v200
	v_and_b32_e32 v206, 0x100, v0
	v_and_b32_e32 v202, 15, v0
	v_lshlrev_b32_e32 v206, 6, v206
	v_lshl_or_b32 v206, v202, 8, v206
	v_and_b32_e32 v202, 0xf0, v0
	v_or_b32_e32 v206, v206, v202
	global_load_dword v179, v204, s[98:99]
	global_load_dword v181, v204, s[98:99] offset:16
	global_load_dword v183, v204, s[100:101]
	global_load_dword v185, v204, s[100:101] offset:16
	global_load_dwordx4 v[192:195], v200, s[50:51]
	global_load_dwordx4 v[222:225], v201, s[50:51]
	global_load_dwordx4 v[226:229], v200, s[50:51] offset:64
	global_load_dwordx4 v[234:237], v200, s[50:51] offset:128
	global_load_dwordx4 v[238:241], v200, s[50:51] offset:192
	global_load_dwordx4 v[242:245], v201, s[50:51] offset:64
	global_load_dwordx4 v[246:249], v201, s[50:51] offset:128
	global_load_dwordx4 v[250:253], v201, s[50:51] offset:192
	s_mul_hi_i32 s74, s44, 0x2aaaaaab
	s_lshl_b32 s74, s74, 15
	s_add_u32 s98, s62, s74
	s_addc_u32 s99, s63, 0
	s_mov_b32 s100, 0x20800
	s_mov_b32 s101, 0x24000
	s_bitcmp1_b32 s73, 8
	s_cselect_b32 s100, s101, s100
	s_and_b32 s74, s73, 0xc0
	s_lshl_b32 s74, s74, 4
	s_add_i32 s100, s100, s74
	s_add_u32 s98, s98, 0x1000
	s_addc_u32 s99, s99, 0
	s_add_i32 m0, s100, 0x0
	s_nop 0
	global_load_lds_dwordx4 v206, s[98:99]
	s_add_u32 s98, s98, 0x1000
	s_addc_u32 s99, s99, 0
	s_add_i32 m0, s100, 0x1000
	s_nop 0
	global_load_lds_dwordx4 v206, s[98:99]
	s_add_u32 s98, s98, 0x1000
	s_addc_u32 s99, s99, 0
	s_add_i32 m0, s100, 0x2000
	s_nop 0
	global_load_lds_dwordx4 v206, s[98:99]
	s_lshl_b32 s74, s6, 11
	s_add_u32 s98, s8, s74
	s_addc_u32 s99, s9, 0
	v_and_b32_e32 v202, 0x7f, v0
	v_lshlrev_b32_e32 v202, 4, v202
	global_load_dwordx4 v[230:233], v202, s[98:99]
	s_waitcnt vmcnt(24)
	s_waitcnt lgkmcnt(0)
	s_barrier
	s_waitcnt lgkmcnt(0)
	.p2align 3
	v_mfma_f32_16x16x32_bf16 v[122:125], v[130:133], v[162:165], v[122:125]
	v_mfma_f32_16x16x32_bf16 v[118:121], v[138:141], v[162:165], v[118:121]
	v_mfma_f32_16x16x32_bf16 v[106:109], v[130:133], v[170:173], v[106:109]
	v_mfma_f32_16x16x32_bf16 v[102:105], v[138:141], v[170:173], v[102:105]
	v_mfma_f32_16x16x32_bf16 v[90:93], v[130:133], v[196:199], v[90:93]
	v_mfma_f32_16x16x32_bf16 v[86:89], v[138:141], v[196:199], v[86:89]
	v_mfma_f32_16x16x32_bf16 v[74:77], v[130:133], v[212:215], v[74:77]
	v_mfma_f32_16x16x32_bf16 v[70:73], v[138:141], v[212:215], v[70:73]
	v_mfma_f32_16x16x32_bf16 v[122:125], v[134:137], v[166:169], v[122:125]
	v_mfma_f32_16x16x32_bf16 v[118:121], v[142:145], v[166:169], v[118:121]
	v_mfma_f32_16x16x32_bf16 v[106:109], v[134:137], v[174:177], v[106:109]
	v_mfma_f32_16x16x32_bf16 v[102:105], v[142:145], v[174:177], v[102:105]
	v_mfma_f32_16x16x32_bf16 v[90:93], v[134:137], v[208:211], v[90:93]
	v_mfma_f32_16x16x32_bf16 v[86:89], v[142:145], v[208:211], v[86:89]
	v_mfma_f32_16x16x32_bf16 v[74:77], v[134:137], v[216:219], v[74:77]
	v_mfma_f32_16x16x32_bf16 v[70:73], v[142:145], v[216:219], v[70:73]
	v_mfma_f32_16x16x32_bf16 v[126:129], v[146:149], v[162:165], v[126:129]
	v_mfma_f32_16x16x32_bf16 v[114:117], v[154:157], v[162:165], v[114:117]
	v_mfma_f32_16x16x32_bf16 v[110:113], v[146:149], v[170:173], v[110:113]
	v_mfma_f32_16x16x32_bf16 v[98:101], v[154:157], v[170:173], v[98:101]
	v_mfma_f32_16x16x32_bf16 v[94:97], v[146:149], v[196:199], v[94:97]
	v_mfma_f32_16x16x32_bf16 v[82:85], v[154:157], v[196:199], v[82:85]
	v_mfma_f32_16x16x32_bf16 v[78:81], v[146:149], v[212:215], v[78:81]
	v_mfma_f32_16x16x32_bf16 v[66:69], v[154:157], v[212:215], v[66:69]
	v_mfma_f32_16x16x32_bf16 v[126:129], v[150:153], v[166:169], v[126:129]
	v_mfma_f32_16x16x32_bf16 v[114:117], v[158:161], v[166:169], v[114:117]
	v_mfma_f32_16x16x32_bf16 v[110:113], v[150:153], v[174:177], v[110:113]
	v_mfma_f32_16x16x32_bf16 v[98:101], v[158:161], v[174:177], v[98:101]
	v_mfma_f32_16x16x32_bf16 v[94:97], v[150:153], v[208:211], v[94:97]
	v_mfma_f32_16x16x32_bf16 v[82:85], v[158:161], v[208:211], v[82:85]
	v_mfma_f32_16x16x32_bf16 v[78:81], v[150:153], v[216:219], v[78:81]
	v_mfma_f32_16x16x32_bf16 v[66:69], v[158:161], v[216:219], v[66:69]
	s_barrier
; #define PG8_STAGE(bufoff, gbase, voff) do { _Pragma("unroll") for (int _i = 0; _i < 2; ++_i) \
;         __builtin_amdgcn_global_load_lds((const unsigned*)((const char*)(gbase) + (voff)[_i]), (PG8_LAS unsigned*)(lds + (bufoff) + ldsw + _i * 8192), 16, 0, 0); } while (0)
; #define PG8_LDA(dst, b, h) do { _Pragma("unroll") for (int m = 0; m < 4; ++m) _Pragma("unroll") for (int k = 0; k < 2; ++k) dst[m][k] = *(const PG8_LAS bf16x8*)(lds + PG8_SA(b, h) + aoff + m * 2048 + k * 1024); } while (0)
; #define PG8_LDB(dst, b, h) do { _Pragma("unroll") for (int n = 0; n < 2; ++n) _Pragma("unroll") for (int k = 0; k < 2; ++k) dst[n][k] = *(const PG8_LAS bf16x8*)(lds + PG8_SB(b, h) + boff + n * 2048 + k * 1024); } while (0)
; #define PG8_MMA(ai, bj, At, Bt) do { __builtin_amdgcn_s_setprio(1); _Pragma("unroll") for (int m = 0; m < 4; ++m) _Pragma("unroll") for (int n = 0; n < 2; ++n) _Pragma("unroll") for (int k = 0; k < 2; ++k) \
;         acc[ai][bj][m][n] = __builtin_amdgcn_mfma_f32_16x16x32_bf16(Bt[n][k], At[m][k], acc[ai][bj][m][n], 0, 0, 0); __builtin_amdgcn_s_setprio(0); } while (0)
; #define PG8_WAIT_V(n) asm volatile("s_waitcnt vmcnt(" #n ")" ::: "memory")
; #define PG8_WAIT_L(n) asm volatile("s_waitcnt lgkmcnt(" #n ")" ::: "memory")
; #define PG8_BAR __builtin_amdgcn_s_barrier()
; #define PG8_SCHED __builtin_amdgcn_sched_barrier(0)
; template <class Epi, class Sched, bool ALIGN_EPI = false, bool SP2 = false>
; __device__ __forceinline__ void gemm_phase(PG8_LAS unsigned char* lds, const Gemm g, const Sched& S, const Epi& E) {
;     ...
;             PG8_WAIT_V(8); PG8_WAIT_L(0); PG8_BAR; PG8_MMA(0, 0, At, B0); PG8_MMA(0, 1, At, B1); PG8_BAR; PG8_SCHED;
;             PG8_LDA(At, 0, 1); PG8_STAGE(PG8_SB(0, 0), b2, voffB); PG8_STAGE(PG8_SB(0, 1), b2 + hstepB, voffB); PG8_STAGE(PG8_SA(0, 0), a2, voffA);
;             PG8_WAIT_V(8); PG8_WAIT_L(0); PG8_BAR; PG8_MMA(1, 0, At, B0); PG8_MMA(1, 1, At, B1); PG8_BAR; PG8_SCHED;
;             PG8_LDB(B0, 1, 0); PG8_LDB(B1, 1, 1); PG8_SCHED; PG8_LDA(At, 1, 0); PG8_STAGE(PG8_SA(0, 1), a2 + hstepA, voffA);
;             PG8_WAIT_V(8); PG8_WAIT_L(0); PG8_BAR; PG8_MMA(0, 0, At, B0); PG8_MMA(0, 1, At, B1); PG8_BAR; PG8_SCHED;
;             PG8_LDA(At, 1, 1); PG8_STAGE(PG8_SB(1, 0), b3, voffB); PG8_STAGE(PG8_SB(1, 1), b3 + hstepB, voffB); PG8_STAGE(PG8_SA(1, 0), a3, voffA);
	s_add_i32 s73, s68, s17
	s_add_u32 s98, s42, 0x80
	s_addc_u32 s99, s43, 0
	s_add_u32 s100, s34, 0x80
	s_addc_u32 s101, s35, 0
	s_mov_b32 m0, s73
	ds_read_b128 v[162:165], v207 offset:16384
	ds_read_b128 v[166:169], v207 offset:17408
	ds_read_b128 v[170:173], v207 offset:18432
	ds_read_b128 v[174:177], v207 offset:19456
	ds_read_b128 v[196:199], v207 offset:20480
	ds_read_b128 v[208:211], v207 offset:21504
	ds_read_b128 v[212:215], v207 offset:22528
	ds_read_b128 v[216:219], v207 offset:23552
	global_load_lds_dwordx4 v182, s[42:43]
	s_add_i32 m0, s73, 0x2000
	s_add_u32 s74, s42, 0x100000
	s_addc_u32 s75, s43, 0
	s_add_i32 s73, s69, s17
	global_load_lds_dwordx4 v178, s[42:43]
	s_mov_b32 m0, s73
	s_nop 0
	global_load_lds_dwordx4 v182, s[74:75]
	s_add_i32 m0, s73, 0x2000
	s_nop 0
	global_load_lds_dwordx4 v178, s[74:75]
	s_mov_b32 m0, s47
	s_nop 0
	global_load_lds_dwordx4 v184, s[34:35]
	s_mov_b32 m0, s48
	s_nop 0
	global_load_lds_dwordx4 v180, s[34:35]
	s_waitcnt vmcnt(24)
	s_waitcnt lgkmcnt(0)
	s_barrier
	s_waitcnt lgkmcnt(0)
	.p2align 3
	v_mfma_f32_16x16x32_bf16 v[58:61], v[130:133], v[162:165], v[58:61]
	v_mfma_f32_16x16x32_bf16 v[54:57], v[138:141], v[162:165], v[54:57]
	v_mfma_f32_16x16x32_bf16 v[42:45], v[130:133], v[170:173], v[42:45]
	v_mfma_f32_16x16x32_bf16 v[38:41], v[138:141], v[170:173], v[38:41]
	v_mfma_f32_16x16x32_bf16 v[26:29], v[130:133], v[196:199], v[26:29]
	v_mfma_f32_16x16x32_bf16 v[22:25], v[138:141], v[196:199], v[22:25]
	v_mfma_f32_16x16x32_bf16 v[10:13], v[130:133], v[212:215], v[10:13]
	v_mfma_f32_16x16x32_bf16 v[6:9], v[138:141], v[212:215], v[6:9]
	v_mfma_f32_16x16x32_bf16 v[58:61], v[134:137], v[166:169], v[58:61]
	v_mfma_f32_16x16x32_bf16 v[54:57], v[142:145], v[166:169], v[54:57]
	v_mfma_f32_16x16x32_bf16 v[42:45], v[134:137], v[174:177], v[42:45]
	v_mfma_f32_16x16x32_bf16 v[38:41], v[142:145], v[174:177], v[38:41]
	v_mfma_f32_16x16x32_bf16 v[26:29], v[134:137], v[208:211], v[26:29]
	v_mfma_f32_16x16x32_bf16 v[22:25], v[142:145], v[208:211], v[22:25]
	v_mfma_f32_16x16x32_bf16 v[10:13], v[134:137], v[216:219], v[10:13]
	v_mfma_f32_16x16x32_bf16 v[6:9], v[142:145], v[216:219], v[6:9]
	v_mfma_f32_16x16x32_bf16 v[62:65], v[146:149], v[162:165], v[62:65]
	v_mfma_f32_16x16x32_bf16 v[50:53], v[154:157], v[162:165], v[50:53]
	v_mfma_f32_16x16x32_bf16 v[46:49], v[146:149], v[170:173], v[46:49]
	v_mfma_f32_16x16x32_bf16 v[34:37], v[154:157], v[170:173], v[34:37]
	v_mfma_f32_16x16x32_bf16 v[30:33], v[146:149], v[196:199], v[30:33]
	v_mfma_f32_16x16x32_bf16 v[18:21], v[154:157], v[196:199], v[18:21]
	v_mfma_f32_16x16x32_bf16 v[14:17], v[146:149], v[212:215], v[14:17]
	v_mfma_f32_16x16x32_bf16 v[2:5], v[154:157], v[212:215], v[2:5]
	v_mfma_f32_16x16x32_bf16 v[62:65], v[150:153], v[166:169], v[62:65]
	v_mfma_f32_16x16x32_bf16 v[50:53], v[158:161], v[166:169], v[50:53]
	v_mfma_f32_16x16x32_bf16 v[46:49], v[150:153], v[174:177], v[46:49]
	v_mfma_f32_16x16x32_bf16 v[34:37], v[158:161], v[174:177], v[34:37]
	v_mfma_f32_16x16x32_bf16 v[30:33], v[150:153], v[208:211], v[30:33]
	v_mfma_f32_16x16x32_bf16 v[18:21], v[158:161], v[208:211], v[18:21]
	v_mfma_f32_16x16x32_bf16 v[14:17], v[150:153], v[216:219], v[14:17]
	v_mfma_f32_16x16x32_bf16 v[2:5], v[158:161], v[216:219], v[2:5]
	s_barrier
	s_add_i32 s73, 0, 0x18000
	s_add_i32 s74, 0, 0x1c000
	v_add_u32_e32 v142, s73, v1
	v_add_u32_e32 v158, s74, v1
	ds_read_b128 v[130:133], v142
	ds_read_b128 v[134:137], v142 offset:1024
	ds_read_b128 v[138:141], v142 offset:2048
	ds_read_b128 v[142:145], v142 offset:3072
	ds_read_b128 v[146:149], v158
	ds_read_b128 v[150:153], v158 offset:1024
	ds_read_b128 v[154:157], v158 offset:2048
	ds_read_b128 v[158:161], v158 offset:3072
	s_add_u32 s34, s34, 0x100000
	s_addc_u32 s35, s35, 0
	s_mov_b32 m0, s49
	ds_read_b128 v[162:165], v207 offset:32768
	ds_read_b128 v[166:169], v207 offset:33792
	ds_read_b128 v[170:173], v207 offset:34816
	ds_read_b128 v[174:177], v207 offset:35840
	ds_read_b128 v[196:199], v207 offset:36864
	ds_read_b128 v[208:211], v207 offset:37888
	ds_read_b128 v[212:215], v207 offset:38912
	ds_read_b128 v[216:219], v207 offset:39936
	global_load_lds_dwordx4 v184, s[34:35]
	s_mov_b32 m0, s60
	s_nop 0
	global_load_lds_dwordx4 v180, s[34:35]
	s_waitcnt vmcnt(24)
	s_waitcnt lgkmcnt(0)
	s_barrier
; #define PG8_STAGE(bufoff, gbase, voff) do { _Pragma("unroll") for (int _i = 0; _i < 2; ++_i) \
;         __builtin_amdgcn_global_load_lds((const unsigned*)((const char*)(gbase) + (voff)[_i]), (PG8_LAS unsigned*)(lds + (bufoff) + ldsw + _i * 8192), 16, 0, 0); } while (0)
; #define PG8_LDA(dst, b, h) do { _Pragma("unroll") for (int m = 0; m < 4; ++m) _Pragma("unroll") for (int k = 0; k < 2; ++k) dst[m][k] = *(const PG8_LAS bf16x8*)(lds + PG8_SA(b, h) + aoff + m * 2048 + k * 1024); } while (0)
; #define PG8_MMA(ai, bj, At, Bt) do { __builtin_amdgcn_s_setprio(1); _Pragma("unroll") for (int m = 0; m < 4; ++m) _Pragma("unroll") for (int n = 0; n < 2; ++n) _Pragma("unroll") for (int k = 0; k < 2; ++k) \
;         acc[ai][bj][m][n] = __builtin_amdgcn_mfma_f32_16x16x32_bf16(Bt[n][k], At[m][k], acc[ai][bj][m][n], 0, 0, 0); __builtin_amdgcn_s_setprio(0); } while (0)
; #define PG8_WAIT_V(n) asm volatile("s_waitcnt vmcnt(" #n ")" ::: "memory")
; #define PG8_WAIT_L(n) asm volatile("s_waitcnt lgkmcnt(" #n ")" ::: "memory")
; #define PG8_BAR __builtin_amdgcn_s_barrier()
; #define PG8_SCHED __builtin_amdgcn_sched_barrier(0)
; template <class Epi, class Sched, bool ALIGN_EPI = false, bool SP2 = false>
; __device__ __forceinline__ void gemm_phase(PG8_LAS unsigned char* lds, const Gemm g, const Sched& S, const Epi& E) {
;     ...
;             PG8_WAIT_V(8); PG8_WAIT_L(0); PG8_BAR; PG8_MMA(0, 0, At, B0); PG8_MMA(0, 1, At, B1); PG8_BAR; PG8_SCHED;
;             PG8_LDA(At, 1, 1); PG8_STAGE(PG8_SB(1, 0), b3, voffB); PG8_STAGE(PG8_SB(1, 1), b3 + hstepB, voffB); PG8_STAGE(PG8_SA(1, 0), a3, voffA);
;             PG8_WAIT_V(8); PG8_WAIT_L(0); PG8_BAR; PG8_MMA(1, 0, At, B0); PG8_MMA(1, 1, At, B1); PG8_BAR; PG8_SCHED;
	s_waitcnt lgkmcnt(0)
	.p2align 3
	v_mfma_f32_16x16x32_bf16 v[122:125], v[130:133], v[162:165], v[122:125]
	v_mfma_f32_16x16x32_bf16 v[118:121], v[138:141], v[162:165], v[118:121]
	v_mfma_f32_16x16x32_bf16 v[106:109], v[130:133], v[170:173], v[106:109]
	v_mfma_f32_16x16x32_bf16 v[102:105], v[138:141], v[170:173], v[102:105]
	v_mfma_f32_16x16x32_bf16 v[90:93], v[130:133], v[196:199], v[90:93]
	v_mfma_f32_16x16x32_bf16 v[86:89], v[138:141], v[196:199], v[86:89]
	v_mfma_f32_16x16x32_bf16 v[74:77], v[130:133], v[212:215], v[74:77]
	v_mfma_f32_16x16x32_bf16 v[70:73], v[138:141], v[212:215], v[70:73]
	v_mfma_f32_16x16x32_bf16 v[122:125], v[134:137], v[166:169], v[122:125]
	v_mfma_f32_16x16x32_bf16 v[118:121], v[142:145], v[166:169], v[118:121]
	v_mfma_f32_16x16x32_bf16 v[106:109], v[134:137], v[174:177], v[106:109]
	v_mfma_f32_16x16x32_bf16 v[102:105], v[142:145], v[174:177], v[102:105]
	v_mfma_f32_16x16x32_bf16 v[90:93], v[134:137], v[208:211], v[90:93]
	v_mfma_f32_16x16x32_bf16 v[86:89], v[142:145], v[208:211], v[86:89]
	v_mfma_f32_16x16x32_bf16 v[74:77], v[134:137], v[216:219], v[74:77]
	v_mfma_f32_16x16x32_bf16 v[70:73], v[142:145], v[216:219], v[70:73]
	v_mfma_f32_16x16x32_bf16 v[126:129], v[146:149], v[162:165], v[126:129]
	v_mfma_f32_16x16x32_bf16 v[114:117], v[154:157], v[162:165], v[114:117]
	v_mfma_f32_16x16x32_bf16 v[110:113], v[146:149], v[170:173], v[110:113]
	v_mfma_f32_16x16x32_bf16 v[98:101], v[154:157], v[170:173], v[98:101]
	v_mfma_f32_16x16x32_bf16 v[94:97], v[146:149], v[196:199], v[94:97]
	v_mfma_f32_16x16x32_bf16 v[82:85], v[154:157], v[196:199], v[82:85]
	v_mfma_f32_16x16x32_bf16 v[78:81], v[146:149], v[212:215], v[78:81]
	v_mfma_f32_16x16x32_bf16 v[66:69], v[154:157], v[212:215], v[66:69]
	v_mfma_f32_16x16x32_bf16 v[126:129], v[150:153], v[166:169], v[126:129]
	v_mfma_f32_16x16x32_bf16 v[114:117], v[158:161], v[166:169], v[114:117]
	v_mfma_f32_16x16x32_bf16 v[110:113], v[150:153], v[174:177], v[110:113]
	v_mfma_f32_16x16x32_bf16 v[98:101], v[158:161], v[174:177], v[98:101]
	v_mfma_f32_16x16x32_bf16 v[94:97], v[150:153], v[208:211], v[94:97]
	v_mfma_f32_16x16x32_bf16 v[82:85], v[158:161], v[208:211], v[82:85]
	v_mfma_f32_16x16x32_bf16 v[78:81], v[150:153], v[216:219], v[78:81]
	v_mfma_f32_16x16x32_bf16 v[66:69], v[158:161], v[216:219], v[66:69]
	s_barrier
	s_add_i32 s34, s73, s17
	s_mov_b32 m0, s34
	ds_read_b128 v[162:165], v207 offset:49152
	ds_read_b128 v[166:169], v207 offset:50176
	ds_read_b128 v[170:173], v207 offset:51200
	ds_read_b128 v[174:177], v207 offset:52224
	ds_read_b128 v[196:199], v207 offset:53248
	ds_read_b128 v[208:211], v207 offset:54272
	ds_read_b128 v[212:215], v207 offset:55296
	ds_read_b128 v[216:219], v207 offset:56320
	global_load_lds_dwordx4 v182, s[98:99]
	s_add_i32 m0, s34, 0x2000
	s_add_u32 s34, s42, 0x100080
	s_addc_u32 s35, s43, 0
	s_add_i32 s42, s74, s17
	global_load_lds_dwordx4 v178, s[98:99]
	s_mov_b32 m0, s42
	s_nop 0
	global_load_lds_dwordx4 v182, s[34:35]
	s_add_i32 m0, s42, 0x2000
	s_nop 0
	global_load_lds_dwordx4 v178, s[34:35]
	s_mov_b32 m0, s64
	s_nop 0
	global_load_lds_dwordx4 v184, s[100:101]
	s_mov_b32 m0, s65
	s_nop 0
	global_load_lds_dwordx4 v180, s[100:101]
	s_waitcnt vmcnt(8)
	s_waitcnt lgkmcnt(0)
	s_barrier
	s_waitcnt lgkmcnt(0)
	.p2align 3
	v_mfma_f32_16x16x32_bf16 v[58:61], v[130:133], v[162:165], v[58:61]
	v_mfma_f32_16x16x32_bf16 v[54:57], v[138:141], v[162:165], v[54:57]
	v_mfma_f32_16x16x32_bf16 v[42:45], v[130:133], v[170:173], v[42:45]
	v_mfma_f32_16x16x32_bf16 v[38:41], v[138:141], v[170:173], v[38:41]
	v_mfma_f32_16x16x32_bf16 v[26:29], v[130:133], v[196:199], v[26:29]
	v_mfma_f32_16x16x32_bf16 v[22:25], v[138:141], v[196:199], v[22:25]
	v_mfma_f32_16x16x32_bf16 v[10:13], v[130:133], v[212:215], v[10:13]
	v_mfma_f32_16x16x32_bf16 v[6:9], v[138:141], v[212:215], v[6:9]
	v_mfma_f32_16x16x32_bf16 v[58:61], v[134:137], v[166:169], v[58:61]
	v_mfma_f32_16x16x32_bf16 v[54:57], v[142:145], v[166:169], v[54:57]
	v_mfma_f32_16x16x32_bf16 v[42:45], v[134:137], v[174:177], v[42:45]
	v_mfma_f32_16x16x32_bf16 v[38:41], v[142:145], v[174:177], v[38:41]
	v_mfma_f32_16x16x32_bf16 v[26:29], v[134:137], v[208:211], v[26:29]
	v_mfma_f32_16x16x32_bf16 v[22:25], v[142:145], v[208:211], v[22:25]
	v_mfma_f32_16x16x32_bf16 v[10:13], v[134:137], v[216:219], v[10:13]
	v_mfma_f32_16x16x32_bf16 v[6:9], v[142:145], v[216:219], v[6:9]
	v_mfma_f32_16x16x32_bf16 v[62:65], v[146:149], v[162:165], v[62:65]
	v_mfma_f32_16x16x32_bf16 v[50:53], v[154:157], v[162:165], v[50:53]
	v_mfma_f32_16x16x32_bf16 v[46:49], v[146:149], v[170:173], v[46:49]
	v_mfma_f32_16x16x32_bf16 v[34:37], v[154:157], v[170:173], v[34:37]
	v_mfma_f32_16x16x32_bf16 v[30:33], v[146:149], v[196:199], v[30:33]
	v_mfma_f32_16x16x32_bf16 v[18:21], v[154:157], v[196:199], v[18:21]
	v_mfma_f32_16x16x32_bf16 v[14:17], v[146:149], v[212:215], v[14:17]
	v_mfma_f32_16x16x32_bf16 v[2:5], v[154:157], v[212:215], v[2:5]
	v_mfma_f32_16x16x32_bf16 v[62:65], v[150:153], v[166:169], v[62:65]
	v_mfma_f32_16x16x32_bf16 v[50:53], v[158:161], v[166:169], v[50:53]
	v_mfma_f32_16x16x32_bf16 v[46:49], v[150:153], v[174:177], v[46:49]
	v_mfma_f32_16x16x32_bf16 v[34:37], v[158:161], v[174:177], v[34:37]
	v_mfma_f32_16x16x32_bf16 v[30:33], v[150:153], v[208:211], v[30:33]
	v_mfma_f32_16x16x32_bf16 v[18:21], v[158:161], v[208:211], v[18:21]
	v_mfma_f32_16x16x32_bf16 v[14:17], v[150:153], v[216:219], v[14:17]
	v_mfma_f32_16x16x32_bf16 v[2:5], v[158:161], v[216:219], v[2:5]
	s_barrier
	s_add_i32 s53, s53, 2
	s_add_u32 s40, s40, 0x100
	s_addc_u32 s41, s41, 0
	s_add_u32 s45, s45, 0x100
	s_addc_u32 s52, s52, 0
	s_setprio 0
	s_and_b64 vcc, exec, s[14:15]
	s_cbranch_vccz .LBB0_1130
	s_barrier

; #define PG8_STAGE(bufoff, gbase, voff) do { _Pragma("unroll") for (int _i = 0; _i < 2; ++_i) \
;         __builtin_amdgcn_global_load_lds((const unsigned*)((const char*)(gbase) + (voff)[_i]), (PG8_LAS unsigned*)(lds + (bufoff) + ldsw + _i * 8192), 16, 0, 0); } while (0)
; #define PG8_LDA(dst, b, h) do { _Pragma("unroll") for (int m = 0; m < 4; ++m) _Pragma("unroll") for (int k = 0; k < 2; ++k) dst[m][k] = *(const PG8_LAS bf16x8*)(lds + PG8_SA(b, h) + aoff + m * 2048 + k * 1024); } while (0)
; #define PG8_LDB(dst, b, h) do { _Pragma("unroll") for (int n = 0; n < 2; ++n) _Pragma("unroll") for (int k = 0; k < 2; ++k) dst[n][k] = *(const PG8_LAS bf16x8*)(lds + PG8_SB(b, h) + boff + n * 2048 + k * 1024); } while (0)
; #define PG8_MMA(ai, bj, At, Bt) do { __builtin_amdgcn_s_setprio(1); _Pragma("unroll") for (int m = 0; m < 4; ++m) _Pragma("unroll") for (int n = 0; n < 2; ++n) _Pragma("unroll") for (int k = 0; k < 2; ++k) \
;         acc[ai][bj][m][n] = __builtin_amdgcn_mfma_f32_16x16x32_bf16(Bt[n][k], At[m][k], acc[ai][bj][m][n], 0, 0, 0); __builtin_amdgcn_s_setprio(0); } while (0)
; #define PG8_WAIT_V(n) asm volatile("s_waitcnt vmcnt(" #n ")" ::: "memory")
; #define PG8_WAIT_L(n) asm volatile("s_waitcnt lgkmcnt(" #n ")" ::: "memory")
; #define PG8_BAR __builtin_amdgcn_s_barrier()
; #define PG8_SCHED __builtin_amdgcn_sched_barrier(0)
; template <class Epi, class Sched, bool ALIGN_EPI = false, bool SP2 = false>
; __device__ __forceinline__ void gemm_phase(PG8_LAS unsigned char* lds, const Gemm g, const Sched& S, const Epi& E) {
;     ...
;             PG8_LDB(B0, 0, 0); PG8_LDB(B1, 0, 1); PG8_SCHED; PG8_LDA(At, 0, 0); PG8_STAGE(PG8_SA(1, 1), a1 + hstepA, voffA);
;             PG8_WAIT_V(8); PG8_WAIT_L(0); PG8_BAR; PG8_MMA(0, 0, At, B0); PG8_MMA(0, 1, At, B1); PG8_BAR; PG8_SCHED;
;             PG8_LDA(At, 0, 1); PG8_STAGE(PG8_SB(0, 0), b2, voffB); PG8_STAGE(PG8_SB(0, 1), b2 + hstepB, voffB); PG8_STAGE(PG8_SA(0, 0), a2, voffA);
;             PG8_WAIT_V(8); PG8_WAIT_L(0); PG8_BAR; PG8_MMA(1, 0, At, B0); PG8_MMA(1, 1, At, B1); PG8_BAR; PG8_SCHED;
.Lsp_LBB0_1206:
.LBB0_1206:
	ds_read_b128 v[130:133], v166
	ds_read_b128 v[134:137], v166 offset:1024
	ds_read_b128 v[138:141], v166 offset:2048
	ds_read_b128 v[142:145], v166 offset:3072
	ds_read_b128 v[170:173], v167
	ds_read_b128 v[174:177], v167 offset:1024
	ds_read_b128 v[178:181], v167 offset:2048
	ds_read_b128 v[182:185], v167 offset:3072
	s_add_u32 s36, s24, 0x100
	s_addc_u32 s37, s25, 0
	s_cmpk_eq_i32 s64, 0xbc
	s_cselect_b32 s35, s7, s37
	s_cselect_b32 s34, s6, s36
	s_cselect_b32 s39, s23, s63
	s_cselect_b32 s38, s22, s62
	s_add_i32 m0, s27, 0xc000
	ds_read_b128 v[186:189], v168
	ds_read_b128 v[190:193], v168 offset:1024
	ds_read_b128 v[194:197], v168 offset:2048
	ds_read_b128 v[198:201], v168 offset:3072
	ds_read_b128 v[202:205], v168 offset:4096
	ds_read_b128 v[206:209], v168 offset:5120
	ds_read_b128 v[210:213], v168 offset:6144
	ds_read_b128 v[214:217], v168 offset:7168
	global_load_lds_dwordx4 v154, s[24:25]
	s_add_i32 m0, s27, 0xe000
	s_nop 0
	global_load_lds_dwordx4 v156, s[24:25]
	s_waitcnt vmcnt(8)
	s_waitcnt lgkmcnt(0)
	s_barrier
	s_waitcnt lgkmcnt(0)
	.p2align 3
	v_mfma_f32_16x16x32_bf16 v[126:129], v[130:133], v[186:189], v[126:129]
	v_mfma_f32_16x16x32_bf16 v[122:125], v[138:141], v[186:189], v[122:125]
	v_mfma_f32_16x16x32_bf16 v[118:121], v[130:133], v[194:197], v[118:121]
	v_mfma_f32_16x16x32_bf16 v[114:117], v[138:141], v[194:197], v[114:117]
	v_mfma_f32_16x16x32_bf16 v[110:113], v[130:133], v[202:205], v[110:113]
	v_mfma_f32_16x16x32_bf16 v[102:105], v[138:141], v[202:205], v[102:105]
	v_mfma_f32_16x16x32_bf16 v[94:97], v[130:133], v[210:213], v[94:97]
	v_mfma_f32_16x16x32_bf16 v[86:89], v[138:141], v[210:213], v[86:89]
	v_mfma_f32_16x16x32_bf16 v[126:129], v[134:137], v[190:193], v[126:129]
	v_mfma_f32_16x16x32_bf16 v[122:125], v[142:145], v[190:193], v[122:125]
	v_mfma_f32_16x16x32_bf16 v[118:121], v[134:137], v[198:201], v[118:121]
	v_mfma_f32_16x16x32_bf16 v[114:117], v[142:145], v[198:201], v[114:117]
	v_mfma_f32_16x16x32_bf16 v[110:113], v[134:137], v[206:209], v[110:113]
	v_mfma_f32_16x16x32_bf16 v[102:105], v[142:145], v[206:209], v[102:105]
	v_mfma_f32_16x16x32_bf16 v[94:97], v[134:137], v[214:217], v[94:97]
	v_mfma_f32_16x16x32_bf16 v[86:89], v[142:145], v[214:217], v[86:89]
	v_mfma_f32_16x16x32_bf16 v[106:109], v[170:173], v[186:189], v[106:109]
	v_mfma_f32_16x16x32_bf16 v[98:101], v[178:181], v[186:189], v[98:101]
	v_mfma_f32_16x16x32_bf16 v[90:93], v[170:173], v[194:197], v[90:93]
	v_mfma_f32_16x16x32_bf16 v[82:85], v[178:181], v[194:197], v[82:85]
	v_mfma_f32_16x16x32_bf16 v[78:81], v[170:173], v[202:205], v[78:81]
	v_mfma_f32_16x16x32_bf16 v[74:77], v[178:181], v[202:205], v[74:77]
	v_mfma_f32_16x16x32_bf16 v[70:73], v[170:173], v[210:213], v[70:73]
	v_mfma_f32_16x16x32_bf16 v[66:69], v[178:181], v[210:213], v[66:69]
	v_mfma_f32_16x16x32_bf16 v[106:109], v[174:177], v[190:193], v[106:109]
	v_mfma_f32_16x16x32_bf16 v[98:101], v[182:185], v[190:193], v[98:101]
	v_mfma_f32_16x16x32_bf16 v[90:93], v[174:177], v[198:201], v[90:93]
	v_mfma_f32_16x16x32_bf16 v[82:85], v[182:185], v[198:201], v[82:85]
	v_mfma_f32_16x16x32_bf16 v[78:81], v[174:177], v[206:209], v[78:81]
	v_mfma_f32_16x16x32_bf16 v[74:77], v[182:185], v[206:209], v[74:77]
	v_mfma_f32_16x16x32_bf16 v[70:73], v[174:177], v[214:217], v[70:73]
	v_mfma_f32_16x16x32_bf16 v[66:69], v[182:185], v[214:217], v[66:69]
	s_barrier
	s_add_i32 s24, s48, s26
	s_add_u32 s98, s38, 0x80
	s_addc_u32 s99, s39, 0
	s_add_u32 s100, s34, 0x80
	s_addc_u32 s101, s35, 0
	s_mov_b32 m0, s24
	ds_read_b128 v[186:189], v168 offset:16384
	ds_read_b128 v[190:193], v168 offset:17408
	ds_read_b128 v[194:197], v168 offset:18432
	ds_read_b128 v[198:201], v168 offset:19456
	ds_read_b128 v[202:205], v168 offset:20480
	ds_read_b128 v[206:209], v168 offset:21504
	ds_read_b128 v[210:213], v168 offset:22528
	ds_read_b128 v[214:217], v168 offset:23552
	global_load_lds_dwordx4 v150, s[38:39]
	s_add_i32 m0, s24, 0x2000
	s_add_u32 s24, s38, 0x300000
	s_addc_u32 s25, s39, 0
	s_add_i32 s65, s49, s26
	global_load_lds_dwordx4 v146, s[38:39]
	s_mov_b32 m0, s65
	s_nop 0
	global_load_lds_dwordx4 v150, s[24:25]
	s_add_i32 m0, s65, 0x2000
	s_nop 0
	global_load_lds_dwordx4 v146, s[24:25]
	s_mov_b32 m0, s27
	s_nop 0
	global_load_lds_dwordx4 v152, s[34:35]
	s_mov_b32 m0, s40
	s_nop 0
	global_load_lds_dwordx4 v148, s[34:35]
	s_waitcnt vmcnt(8)
	s_waitcnt lgkmcnt(0)
	s_barrier
	s_waitcnt lgkmcnt(0)
	.p2align 3
	v_mfma_f32_16x16x32_bf16 v[62:65], v[130:133], v[186:189], v[62:65]
	v_mfma_f32_16x16x32_bf16 v[58:61], v[138:141], v[186:189], v[58:61]
	v_mfma_f32_16x16x32_bf16 v[50:53], v[130:133], v[194:197], v[50:53]
	v_mfma_f32_16x16x32_bf16 v[42:45], v[138:141], v[194:197], v[42:45]
	v_mfma_f32_16x16x32_bf16 v[34:37], v[130:133], v[202:205], v[34:37]
	v_mfma_f32_16x16x32_bf16 v[26:29], v[138:141], v[202:205], v[26:29]
	v_mfma_f32_16x16x32_bf16 v[18:21], v[130:133], v[210:213], v[18:21]
	v_mfma_f32_16x16x32_bf16 v[10:13], v[138:141], v[210:213], v[10:13]
	v_mfma_f32_16x16x32_bf16 v[62:65], v[134:137], v[190:193], v[62:65]
	v_mfma_f32_16x16x32_bf16 v[58:61], v[142:145], v[190:193], v[58:61]
	v_mfma_f32_16x16x32_bf16 v[50:53], v[134:137], v[198:201], v[50:53]
	v_mfma_f32_16x16x32_bf16 v[42:45], v[142:145], v[198:201], v[42:45]
	v_mfma_f32_16x16x32_bf16 v[34:37], v[134:137], v[206:209], v[34:37]
	v_mfma_f32_16x16x32_bf16 v[26:29], v[142:145], v[206:209], v[26:29]
	v_mfma_f32_16x16x32_bf16 v[18:21], v[134:137], v[214:217], v[18:21]
	v_mfma_f32_16x16x32_bf16 v[10:13], v[142:145], v[214:217], v[10:13]
	v_mfma_f32_16x16x32_bf16 v[54:57], v[170:173], v[186:189], v[54:57]
	v_mfma_f32_16x16x32_bf16 v[46:49], v[178:181], v[186:189], v[46:49]
	v_mfma_f32_16x16x32_bf16 v[38:41], v[170:173], v[194:197], v[38:41]
	v_mfma_f32_16x16x32_bf16 v[30:33], v[178:181], v[194:197], v[30:33]
	v_mfma_f32_16x16x32_bf16 v[22:25], v[170:173], v[202:205], v[22:25]
	v_mfma_f32_16x16x32_bf16 v[14:17], v[178:181], v[202:205], v[14:17]
	v_mfma_f32_16x16x32_bf16 v[6:9], v[170:173], v[210:213], v[6:9]
	v_mfma_f32_16x16x32_bf16 v[2:5], v[178:181], v[210:213], v[2:5]
	v_mfma_f32_16x16x32_bf16 v[54:57], v[174:177], v[190:193], v[54:57]
	v_mfma_f32_16x16x32_bf16 v[46:49], v[182:185], v[190:193], v[46:49]
	v_mfma_f32_16x16x32_bf16 v[38:41], v[174:177], v[198:201], v[38:41]
	v_mfma_f32_16x16x32_bf16 v[30:33], v[182:185], v[198:201], v[30:33]
	v_mfma_f32_16x16x32_bf16 v[22:25], v[174:177], v[206:209], v[22:25]
	v_mfma_f32_16x16x32_bf16 v[14:17], v[182:185], v[206:209], v[14:17]
	v_mfma_f32_16x16x32_bf16 v[6:9], v[174:177], v[214:217], v[6:9]
	v_mfma_f32_16x16x32_bf16 v[2:5], v[182:185], v[214:217], v[2:5]
	s_barrier
; #define PG8_STAGE(bufoff, gbase, voff) do { _Pragma("unroll") for (int _i = 0; _i < 2; ++_i) \
;         __builtin_amdgcn_global_load_lds((const unsigned*)((const char*)(gbase) + (voff)[_i]), (PG8_LAS unsigned*)(lds + (bufoff) + ldsw + _i * 8192), 16, 0, 0); } while (0)
; #define PG8_LDA(dst, b, h) do { _Pragma("unroll") for (int m = 0; m < 4; ++m) _Pragma("unroll") for (int k = 0; k < 2; ++k) dst[m][k] = *(const PG8_LAS bf16x8*)(lds + PG8_SA(b, h) + aoff + m * 2048 + k * 1024); } while (0)
; #define PG8_LDB(dst, b, h) do { _Pragma("unroll") for (int n = 0; n < 2; ++n) _Pragma("unroll") for (int k = 0; k < 2; ++k) dst[n][k] = *(const PG8_LAS bf16x8*)(lds + PG8_SB(b, h) + boff + n * 2048 + k * 1024); } while (0)
; #define PG8_MMA(ai, bj, At, Bt) do { __builtin_amdgcn_s_setprio(1); _Pragma("unroll") for (int m = 0; m < 4; ++m) _Pragma("unroll") for (int n = 0; n < 2; ++n) _Pragma("unroll") for (int k = 0; k < 2; ++k) \
;         acc[ai][bj][m][n] = __builtin_amdgcn_mfma_f32_16x16x32_bf16(Bt[n][k], At[m][k], acc[ai][bj][m][n], 0, 0, 0); __builtin_amdgcn_s_setprio(0); } while (0)
; #define PG8_WAIT_V(n) asm volatile("s_waitcnt vmcnt(" #n ")" ::: "memory")
; #define PG8_WAIT_L(n) asm volatile("s_waitcnt lgkmcnt(" #n ")" ::: "memory")
; #define PG8_BAR __builtin_amdgcn_s_barrier()
; #define PG8_SCHED __builtin_amdgcn_sched_barrier(0)
; template <class Epi, class Sched, bool ALIGN_EPI = false, bool SP2 = false>
; __device__ __forceinline__ void gemm_phase(PG8_LAS unsigned char* lds, const Gemm g, const Sched& S, const Epi& E) {
;     ...
;         for (int t = 0; t < nt; t += 2) {
;     ...
;             PG8_LDB(B0, 1, 0); PG8_LDB(B1, 1, 1); PG8_SCHED; PG8_LDA(At, 1, 0); PG8_STAGE(PG8_SA(0, 1), a2 + hstepA, voffA);
;             PG8_WAIT_V(8); PG8_WAIT_L(0); PG8_BAR; PG8_MMA(0, 0, At, B0); PG8_MMA(0, 1, At, B1); PG8_BAR; PG8_SCHED;
;             PG8_LDA(At, 1, 1); PG8_STAGE(PG8_SB(1, 0), b3, voffB); PG8_STAGE(PG8_SB(1, 1), b3 + hstepB, voffB); PG8_STAGE(PG8_SA(1, 0), a3, voffA);
;             PG8_WAIT_V(8); PG8_WAIT_L(0); PG8_BAR; PG8_MMA(1, 0, At, B0); PG8_MMA(1, 1, At, B1); PG8_BAR; PG8_SCHED;
	s_add_i32 s65, 0, 0x18000
	s_add_i32 s66, 0, 0x1c000
	v_add_u32_e32 v142, s65, v164
	v_add_u32_e32 v169, s66, v164
	ds_read_b128 v[130:133], v142
	ds_read_b128 v[134:137], v142 offset:1024
	ds_read_b128 v[138:141], v142 offset:2048
	ds_read_b128 v[142:145], v142 offset:3072
	ds_read_b128 v[170:173], v169
	ds_read_b128 v[174:177], v169 offset:1024
	ds_read_b128 v[178:181], v169 offset:2048
	ds_read_b128 v[182:185], v169 offset:3072
	s_add_u32 s24, s34, 0x300000
	s_addc_u32 s25, s35, 0
	s_mov_b32 m0, s41
	ds_read_b128 v[186:189], v168 offset:32768
	ds_read_b128 v[190:193], v168 offset:33792
	ds_read_b128 v[194:197], v168 offset:34816
	ds_read_b128 v[198:201], v168 offset:35840
	ds_read_b128 v[202:205], v168 offset:36864
	ds_read_b128 v[206:209], v168 offset:37888
	ds_read_b128 v[210:213], v168 offset:38912
	ds_read_b128 v[214:217], v168 offset:39936
	global_load_lds_dwordx4 v152, s[24:25]
	s_mov_b32 m0, s42
	s_nop 0
	global_load_lds_dwordx4 v148, s[24:25]
	s_waitcnt vmcnt(8)
	s_waitcnt lgkmcnt(0)
	s_barrier
	s_waitcnt lgkmcnt(0)
	.p2align 3
	v_mfma_f32_16x16x32_bf16 v[126:129], v[130:133], v[186:189], v[126:129]
	v_mfma_f32_16x16x32_bf16 v[122:125], v[138:141], v[186:189], v[122:125]
	v_mfma_f32_16x16x32_bf16 v[118:121], v[130:133], v[194:197], v[118:121]
	v_mfma_f32_16x16x32_bf16 v[114:117], v[138:141], v[194:197], v[114:117]
	v_mfma_f32_16x16x32_bf16 v[110:113], v[130:133], v[202:205], v[110:113]
	v_mfma_f32_16x16x32_bf16 v[102:105], v[138:141], v[202:205], v[102:105]
	v_mfma_f32_16x16x32_bf16 v[94:97], v[130:133], v[210:213], v[94:97]
	v_mfma_f32_16x16x32_bf16 v[86:89], v[138:141], v[210:213], v[86:89]
	v_mfma_f32_16x16x32_bf16 v[126:129], v[134:137], v[190:193], v[126:129]
	v_mfma_f32_16x16x32_bf16 v[122:125], v[142:145], v[190:193], v[122:125]
	v_mfma_f32_16x16x32_bf16 v[118:121], v[134:137], v[198:201], v[118:121]
	v_mfma_f32_16x16x32_bf16 v[114:117], v[142:145], v[198:201], v[114:117]
	v_mfma_f32_16x16x32_bf16 v[110:113], v[134:137], v[206:209], v[110:113]
	v_mfma_f32_16x16x32_bf16 v[102:105], v[142:145], v[206:209], v[102:105]
	v_mfma_f32_16x16x32_bf16 v[94:97], v[134:137], v[214:217], v[94:97]
	v_mfma_f32_16x16x32_bf16 v[86:89], v[142:145], v[214:217], v[86:89]
	v_mfma_f32_16x16x32_bf16 v[106:109], v[170:173], v[186:189], v[106:109]
	v_mfma_f32_16x16x32_bf16 v[98:101], v[178:181], v[186:189], v[98:101]
	v_mfma_f32_16x16x32_bf16 v[90:93], v[170:173], v[194:197], v[90:93]
	v_mfma_f32_16x16x32_bf16 v[82:85], v[178:181], v[194:197], v[82:85]
	v_mfma_f32_16x16x32_bf16 v[78:81], v[170:173], v[202:205], v[78:81]
	v_mfma_f32_16x16x32_bf16 v[74:77], v[178:181], v[202:205], v[74:77]
	v_mfma_f32_16x16x32_bf16 v[70:73], v[170:173], v[210:213], v[70:73]
	v_mfma_f32_16x16x32_bf16 v[66:69], v[178:181], v[210:213], v[66:69]
	v_mfma_f32_16x16x32_bf16 v[106:109], v[174:177], v[190:193], v[106:109]
	v_mfma_f32_16x16x32_bf16 v[98:101], v[182:185], v[190:193], v[98:101]
	v_mfma_f32_16x16x32_bf16 v[90:93], v[174:177], v[198:201], v[90:93]
	v_mfma_f32_16x16x32_bf16 v[82:85], v[182:185], v[198:201], v[82:85]
	v_mfma_f32_16x16x32_bf16 v[78:81], v[174:177], v[206:209], v[78:81]
	v_mfma_f32_16x16x32_bf16 v[74:77], v[182:185], v[206:209], v[74:77]
	v_mfma_f32_16x16x32_bf16 v[70:73], v[174:177], v[214:217], v[70:73]
	v_mfma_f32_16x16x32_bf16 v[66:69], v[182:185], v[214:217], v[66:69]
	s_barrier
	s_add_i32 s24, s65, s26
	s_mov_b32 m0, s24
	ds_read_b128 v[186:189], v168 offset:49152
	ds_read_b128 v[190:193], v168 offset:50176
	ds_read_b128 v[194:197], v168 offset:51200
	ds_read_b128 v[198:201], v168 offset:52224
	ds_read_b128 v[202:205], v168 offset:53248
	ds_read_b128 v[206:209], v168 offset:54272
	ds_read_b128 v[210:213], v168 offset:55296
	ds_read_b128 v[214:217], v168 offset:56320
	global_load_lds_dwordx4 v150, s[98:99]
	s_add_i32 m0, s24, 0x2000
	s_add_u32 s24, s38, 0x300080
	s_addc_u32 s25, s39, 0
	s_add_i32 s34, s66, s26
	global_load_lds_dwordx4 v146, s[98:99]
	s_mov_b32 m0, s34
	s_nop 0
	global_load_lds_dwordx4 v150, s[24:25]
	s_add_i32 m0, s34, 0x2000
	s_nop 0
	global_load_lds_dwordx4 v146, s[24:25]
	s_mov_b32 m0, s46
	s_nop 0
	global_load_lds_dwordx4 v152, s[100:101]
	s_mov_b32 m0, s47
	s_nop 0
	global_load_lds_dwordx4 v148, s[100:101]
	s_waitcnt vmcnt(8)
	s_waitcnt lgkmcnt(0)
	s_barrier
	s_waitcnt lgkmcnt(0)
	.p2align 3
	v_mfma_f32_16x16x32_bf16 v[62:65], v[130:133], v[186:189], v[62:65]
	v_mfma_f32_16x16x32_bf16 v[58:61], v[138:141], v[186:189], v[58:61]
	v_mfma_f32_16x16x32_bf16 v[50:53], v[130:133], v[194:197], v[50:53]
	v_mfma_f32_16x16x32_bf16 v[42:45], v[138:141], v[194:197], v[42:45]
	v_mfma_f32_16x16x32_bf16 v[34:37], v[130:133], v[202:205], v[34:37]
	v_mfma_f32_16x16x32_bf16 v[26:29], v[138:141], v[202:205], v[26:29]
	v_mfma_f32_16x16x32_bf16 v[18:21], v[130:133], v[210:213], v[18:21]
	v_mfma_f32_16x16x32_bf16 v[10:13], v[138:141], v[210:213], v[10:13]
	v_mfma_f32_16x16x32_bf16 v[62:65], v[134:137], v[190:193], v[62:65]
	v_mfma_f32_16x16x32_bf16 v[58:61], v[142:145], v[190:193], v[58:61]
	v_mfma_f32_16x16x32_bf16 v[50:53], v[134:137], v[198:201], v[50:53]
	v_mfma_f32_16x16x32_bf16 v[42:45], v[142:145], v[198:201], v[42:45]
	v_mfma_f32_16x16x32_bf16 v[34:37], v[134:137], v[206:209], v[34:37]
	v_mfma_f32_16x16x32_bf16 v[26:29], v[142:145], v[206:209], v[26:29]
	v_mfma_f32_16x16x32_bf16 v[18:21], v[134:137], v[214:217], v[18:21]
	v_mfma_f32_16x16x32_bf16 v[10:13], v[142:145], v[214:217], v[10:13]
	v_mfma_f32_16x16x32_bf16 v[54:57], v[170:173], v[186:189], v[54:57]
	v_mfma_f32_16x16x32_bf16 v[46:49], v[178:181], v[186:189], v[46:49]
	v_mfma_f32_16x16x32_bf16 v[38:41], v[170:173], v[194:197], v[38:41]
	v_mfma_f32_16x16x32_bf16 v[30:33], v[178:181], v[194:197], v[30:33]
	v_mfma_f32_16x16x32_bf16 v[22:25], v[170:173], v[202:205], v[22:25]
	v_mfma_f32_16x16x32_bf16 v[14:17], v[178:181], v[202:205], v[14:17]
	v_mfma_f32_16x16x32_bf16 v[6:9], v[170:173], v[210:213], v[6:9]
	v_mfma_f32_16x16x32_bf16 v[2:5], v[178:181], v[210:213], v[2:5]
	v_mfma_f32_16x16x32_bf16 v[54:57], v[174:177], v[190:193], v[54:57]
	v_mfma_f32_16x16x32_bf16 v[46:49], v[182:185], v[190:193], v[46:49]
	v_mfma_f32_16x16x32_bf16 v[38:41], v[174:177], v[198:201], v[38:41]
	v_mfma_f32_16x16x32_bf16 v[30:33], v[182:185], v[198:201], v[30:33]
	v_mfma_f32_16x16x32_bf16 v[22:25], v[174:177], v[206:209], v[22:25]
	v_mfma_f32_16x16x32_bf16 v[14:17], v[182:185], v[206:209], v[14:17]
	v_mfma_f32_16x16x32_bf16 v[6:9], v[174:177], v[214:217], v[6:9]
	v_mfma_f32_16x16x32_bf16 v[2:5], v[182:185], v[214:217], v[2:5]
	s_barrier
	s_add_i32 s64, s64, 2
	s_add_u32 s62, s62, 0x100
	s_addc_u32 s63, s63, 0
	s_cmpk_gt_u32 s64, 0xbd
	s_mov_b64 s[24:25], s[36:37]
	s_cbranch_scc0 .LBB0_1206
	s_setprio 0
	s_and_b64 vcc, exec, s[12:13]
	s_cbranch_vccz .LBB0_1209
	s_barrier
